# P2 pooling rewritten by hand: each row loaded once (sliding window), masked doubling-tree window sums in f32, 3.5x fewer VALU ops; original path kept as fallback for other grid shapes
# speedup vs baseline: 1.0293x; 1.0145x over previous
; __global__ void __launch_bounds__(NTHR, 2) hybrid_fwd(Args args) {
;     ...
;         const int rpb = (T + G - 1) / G, rows_per = (rpb + NWAVES - 1) / NWAVES;
;         const int gI = lane >> 4, w = 2 << gI;
;         const int t_b = hb * rpb + wave * rows_per; int nr = rpb - wave * rows_per; if (nr > rows_per) nr = rows_per; if (t_b + nr > T) nr = T - t_b;
;         u32x4 qn[16];
;         if (nr > 0) { const int sp0 = t_b & 2047, c0_ = (sp0 + 1) < w ? (sp0 + 1) : w;
; #pragma unroll
;             for (int j = 0; j < 16; ++j) qn[j] = *(const u32x4*)(UB + (size_t)(j < c0_ ? t_b - j : t_b) * 512 + lane * 8); }
;         for (int i = 0; i < nr; ++i) { const int t = t_b + i;
;             const int sp = t & 2047, cnt = (sp + 1) < w ? (sp + 1) : w;
;             u32x4 qv[16];
; #pragma unroll
;             for (int j = 0; j < 16; ++j) qv[j] = qn[j];
;             if (i + 1 < nr) { const int t1 = t + 1, sp1 = t1 & 2047, c1_ = (sp1 + 1) < w ? (sp1 + 1) : w;
; #pragma unroll
;                 for (int j = 0; j < 16; ++j) qn[j] = *(const u32x4*)(UB + (size_t)(j < c1_ ? t1 - j : t1) * 512 + lane * 8); }
.LBB0_372:
	s_add_i32 s25, s20, 0x7fff
	s_waitcnt lgkmcnt(0)
	s_waitcnt lgkmcnt(0)
	s_waitcnt lgkmcnt(0)
	s_waitcnt lgkmcnt(0)
	s_waitcnt lgkmcnt(0)
	s_waitcnt lgkmcnt(0)
	s_waitcnt lgkmcnt(0)
	s_waitcnt lgkmcnt(0)
	s_waitcnt lgkmcnt(0)
	s_waitcnt lgkmcnt(0)
	s_waitcnt lgkmcnt(0)
	s_waitcnt lgkmcnt(0)
	s_waitcnt lgkmcnt(0)
	s_waitcnt lgkmcnt(0)
	s_waitcnt lgkmcnt(0)
	s_waitcnt lgkmcnt(0)
	s_waitcnt lgkmcnt(0)
	s_waitcnt lgkmcnt(0)
	s_waitcnt lgkmcnt(0)
	s_abs_i32 s61, s20
	v_cvt_f32_u32_e32 v1, s61
	s_sub_i32 s27, 0, s61
	s_waitcnt lgkmcnt(0)
	v_rcp_iflag_f32_e32 v1, v1
	s_ashr_i32 s26, s25, 31
	s_abs_i32 s25, s25
	v_mul_f32_e32 v1, 0x4f7ffffe, v1
	v_cvt_u32_f32_e32 v1, v1
	s_xor_b32 s26, s26, s21
	s_mov_b32 s28, 1
	v_readfirstlane_b32 s62, v1
	s_mul_i32 s27, s27, s62
	s_mul_hi_u32 s10, s62, s27
	s_add_i32 s62, s62, s10
	s_mul_hi_u32 s10, s25, s62
	s_mul_i32 s11, s10, s61
	s_sub_i32 s11, s25, s11
	s_add_i32 s14, s10, 1
	s_sub_i32 s15, s11, s61
	s_cmp_ge_u32 s11, s61
	s_cselect_b32 s10, s14, s10
	s_cselect_b32 s11, s15, s11
	s_add_i32 s14, s10, 1
	s_cmp_ge_u32 s11, s61
	s_cselect_b32 s10, s14, s10
	s_xor_b32 s10, s10, s26
	s_sub_i32 s56, s10, s26
	s_add_i32 s10, s56, 7
	s_ashr_i32 s14, s10, 31
	s_lshr_b32 s14, s14, 29
	s_add_i32 s10, s10, s14
	s_ashr_i32 s14, s10, 3
	s_mul_i32 s11, s56, s24
	s_mul_i32 s15, s14, s74
	s_add_i32 s10, s15, s11
	s_sub_i32 s11, s56, s15
	s_min_i32 s57, s11, s14
	s_add_i32 s11, s57, s10
	s_sub_i32 s14, 0x8000, s10
	s_cmp_gt_i32 s11, 0x8000
	s_cselect_b32 s29, s14, s57
	v_mov_b32_e32 v0, v212
	s_cmp_lt_i32 s29, 1
	v_writelane_b32 v248, s15, 5
	s_cbranch_scc1 .LBB0_377
	s_cmp_lg_u32 s29, 16
	s_cbranch_scc1 .Lpool_orig
	s_and_b32 s98, s10, 15
	s_cmp_lg_u32 s98, 0
	s_cbranch_scc1 .Lpool_orig
	v_lshlrev_b32_e32 v0, 4, v212
	v_mov_b32_e32 v1, 0
	s_lshl_b32 s98, s10, 10
	s_add_u32 s14, s8, 0x15c00000
	s_addc_u32 s15, s9, 0
	s_add_u32 s14, s14, s98
	s_addc_u32 s15, s15, 0
	s_and_b32 s99, s10, 0x7ff
	s_sub_u32 s26, s14, 0x3000
	s_subb_u32 s27, s15, 0
	v_lshl_add_u64 v[2:3], s[26:27], 0, v[0:1]
	s_sub_u32 s26, s14, 0x1000
	s_subb_u32 s27, s15, 0
	v_lshl_add_u64 v[4:5], s[26:27], 0, v[0:1]
	s_add_u32 s26, s14, 0x1000
	s_addc_u32 s27, s15, 0
	v_lshl_add_u64 v[6:7], s[26:27], 0, v[0:1]
	s_add_u32 s26, s14, 0x3000
	s_addc_u32 s27, s15, 0
	v_lshl_add_u64 v[132:133], s[26:27], 0, v[0:1]
	s_cmp_eq_u32 s99, 0
	s_cbranch_scc1 .Lpool_ld_seqstart
	global_load_dwordx4 v[8:11], v[2:3], off offset:-3072
	global_load_dwordx4 v[12:15], v[2:3], off offset:-2048
	global_load_dwordx4 v[16:19], v[2:3], off offset:-1024
	global_load_dwordx4 v[20:23], v[2:3], off
	global_load_dwordx4 v[24:27], v[2:3], off offset:1024
	global_load_dwordx4 v[28:31], v[2:3], off offset:2048
	global_load_dwordx4 v[32:35], v[2:3], off offset:3072
	global_load_dwordx4 v[36:39], v[4:5], off offset:-4096
	global_load_dwordx4 v[40:43], v[4:5], off offset:-3072
	global_load_dwordx4 v[44:47], v[4:5], off offset:-2048
	global_load_dwordx4 v[48:51], v[4:5], off offset:-1024
	global_load_dwordx4 v[52:55], v[4:5], off
	global_load_dwordx4 v[56:59], v[4:5], off offset:1024
	global_load_dwordx4 v[60:63], v[4:5], off offset:2048
	global_load_dwordx4 v[64:67], v[4:5], off offset:3072
	global_load_dwordx4 v[68:71], v[6:7], off offset:-4096
	global_load_dwordx4 v[72:75], v[6:7], off offset:-3072
	global_load_dwordx4 v[76:79], v[6:7], off offset:-2048
	global_load_dwordx4 v[80:83], v[6:7], off offset:-1024
	global_load_dwordx4 v[84:87], v[6:7], off
	global_load_dwordx4 v[88:91], v[6:7], off offset:1024
	global_load_dwordx4 v[92:95], v[6:7], off offset:2048
	global_load_dwordx4 v[96:99], v[6:7], off offset:3072
	global_load_dwordx4 v[100:103], v[132:133], off offset:-4096
	global_load_dwordx4 v[104:107], v[132:133], off offset:-3072
	global_load_dwordx4 v[108:111], v[132:133], off offset:-2048
	global_load_dwordx4 v[112:115], v[132:133], off offset:-1024
	global_load_dwordx4 v[116:119], v[132:133], off
	global_load_dwordx4 v[120:123], v[132:133], off offset:1024
	global_load_dwordx4 v[124:127], v[132:133], off offset:2048
	global_load_dwordx4 v[128:131], v[132:133], off offset:3072
	s_branch .Lpool_ld_done
.Lpool_ld_seqstart:
	global_load_dwordx4 v[68:71], v[6:7], off offset:-4096
	global_load_dwordx4 v[72:75], v[6:7], off offset:-3072
	global_load_dwordx4 v[76:79], v[6:7], off offset:-2048
	global_load_dwordx4 v[80:83], v[6:7], off offset:-1024
	global_load_dwordx4 v[84:87], v[6:7], off
	global_load_dwordx4 v[88:91], v[6:7], off offset:1024
	global_load_dwordx4 v[92:95], v[6:7], off offset:2048
	global_load_dwordx4 v[96:99], v[6:7], off offset:3072
	global_load_dwordx4 v[100:103], v[132:133], off offset:-4096
	global_load_dwordx4 v[104:107], v[132:133], off offset:-3072
	global_load_dwordx4 v[108:111], v[132:133], off offset:-2048
	global_load_dwordx4 v[112:115], v[132:133], off offset:-1024
	global_load_dwordx4 v[116:119], v[132:133], off
	global_load_dwordx4 v[120:123], v[132:133], off offset:1024
	global_load_dwordx4 v[124:127], v[132:133], off offset:2048
	global_load_dwordx4 v[128:131], v[132:133], off offset:3072
	v_mov_b32_e32 v8, 0
	v_mov_b32_e32 v9, 0
	v_mov_b32_e32 v10, 0
	v_mov_b32_e32 v11, 0
	v_mov_b32_e32 v12, 0
	v_mov_b32_e32 v13, 0
	v_mov_b32_e32 v14, 0
	v_mov_b32_e32 v15, 0
	v_mov_b32_e32 v16, 0
	v_mov_b32_e32 v17, 0
	v_mov_b32_e32 v18, 0
	v_mov_b32_e32 v19, 0
	v_mov_b32_e32 v20, 0
	v_mov_b32_e32 v21, 0
	v_mov_b32_e32 v22, 0
	v_mov_b32_e32 v23, 0
	v_mov_b32_e32 v24, 0
	v_mov_b32_e32 v25, 0
	v_mov_b32_e32 v26, 0
	v_mov_b32_e32 v27, 0
	v_mov_b32_e32 v28, 0
	v_mov_b32_e32 v29, 0
	v_mov_b32_e32 v30, 0
	v_mov_b32_e32 v31, 0
	v_mov_b32_e32 v32, 0
	v_mov_b32_e32 v33, 0
	v_mov_b32_e32 v34, 0
	v_mov_b32_e32 v35, 0
	v_mov_b32_e32 v36, 0
	v_mov_b32_e32 v37, 0
	v_mov_b32_e32 v38, 0
	v_mov_b32_e32 v39, 0
	v_mov_b32_e32 v40, 0
	v_mov_b32_e32 v41, 0
	v_mov_b32_e32 v42, 0
	v_mov_b32_e32 v43, 0
	v_mov_b32_e32 v44, 0
	v_mov_b32_e32 v45, 0
	v_mov_b32_e32 v46, 0
	v_mov_b32_e32 v47, 0
	v_mov_b32_e32 v48, 0
	v_mov_b32_e32 v49, 0
	v_mov_b32_e32 v50, 0
	v_mov_b32_e32 v51, 0
	v_mov_b32_e32 v52, 0
	v_mov_b32_e32 v53, 0
	v_mov_b32_e32 v54, 0
	v_mov_b32_e32 v55, 0
	v_mov_b32_e32 v56, 0
	v_mov_b32_e32 v57, 0
	v_mov_b32_e32 v58, 0
	v_mov_b32_e32 v59, 0
	v_mov_b32_e32 v60, 0
	v_mov_b32_e32 v61, 0
	v_mov_b32_e32 v62, 0
	v_mov_b32_e32 v63, 0
	v_mov_b32_e32 v64, 0
	v_mov_b32_e32 v65, 0
	v_mov_b32_e32 v66, 0
	v_mov_b32_e32 v67, 0
; __device__ __forceinline__ unsigned pk2(float lo, float hi) { return pg8::cvt_pk_bf16(lo, hi); }
; __global__ void __launch_bounds__(NTHR, 2) hybrid_fwd(Args args) {
;     ...
;             float a[8];
; #pragma unroll
;             for (int e = 0; e < 8; ++e) a[e] = 0.f;
;             const u32x4 u0 = qv[0];
; #pragma unroll
;             for (int j = 0; j < 16; ++j) { const float mk = j < cnt ? 1.0f : 0.0f; const u32x4 q = qv[j];
;                 a[0] += mk * bflo(q.x); a[1] += mk * bfhi(q.x); a[2] += mk * bflo(q.y); a[3] += mk * bfhi(q.y); a[4] += mk * bflo(q.z); a[5] += mk * bfhi(q.z); a[6] += mk * bflo(q.w); a[7] += mk * bfhi(q.w); }
;             const float ic = 1.0f / (float)cnt;
;             u32x4 o; o.x = pk2(a[0] * ic - bflo(u0.x), a[1] * ic - bfhi(u0.x)); o.y = pk2(a[2] * ic - bflo(u0.y), a[3] * ic - bfhi(u0.y));
;             o.z = pk2(a[4] * ic - bflo(u0.z), a[5] * ic - bfhi(u0.z)); o.w = pk2(a[6] * ic - bflo(u0.w), a[7] * ic - bfhi(u0.w));
.Lpool_ld_done:
	v_lshrrev_b32_e32 v137, 4, v212
	v_cmp_lt_u32_e32 vcc, 0, v137
	s_nop 1
	v_cndmask_b32_e64 v134, 0, 1.0, vcc
	v_cmp_lt_u32_e32 vcc, 1, v137
	s_nop 1
	v_cndmask_b32_e64 v135, 0, 1.0, vcc
	v_cmp_lt_u32_e32 vcc, 2, v137
	s_nop 1
	v_cndmask_b32_e64 v136, 0, 1.0, vcc
	v_lshlrev_b32_e64 v137, v137, 2
	s_lshl_b32 s98, s10, 11
	s_add_u32 s26, s8, 0x3c00000
	s_addc_u32 s27, s9, 0
	s_add_u32 s26, s26, s98
	s_addc_u32 s27, s27, 0
	v_lshl_add_u64 v[138:139], s[26:27], 0, v[0:1]
	s_mov_b32 s100, 0xffff0000
	s_mov_b64 s[26:27], 0x1000
	s_waitcnt vmcnt(0)
	v_mov_b32_e32 v175, 0
	v_mov_b32_e32 v176, 0
	v_mov_b32_e32 v177, 0
	v_mov_b32_e32 v178, 0
	v_mov_b32_e32 v179, 0
	v_mov_b32_e32 v180, 0
	v_mov_b32_e32 v181, 0
	v_mov_b32_e32 v182, 0
	v_mov_b32_e32 v183, 0
	v_mov_b32_e32 v184, 0
	v_mov_b32_e32 v185, 0
	v_mov_b32_e32 v186, 0
	v_mov_b32_e32 v187, 0
	v_mov_b32_e32 v188, 0
	v_mov_b32_e32 v189, 0
	v_mov_b32_e32 v190, 0
	v_mov_b32_e32 v191, 0
	v_mov_b32_e32 v192, 0
	v_mov_b32_e32 v193, 0
	v_mov_b32_e32 v194, 0
	v_mov_b32_e32 v195, 0
	v_mov_b32_e32 v196, 0
	v_mov_b32_e32 v197, 0
	v_mov_b32_e32 v198, 0
	v_mov_b32_e32 v199, 0
	v_mov_b32_e32 v200, 0
	v_mov_b32_e32 v201, 0
	v_mov_b32_e32 v202, 0
	v_mov_b32_e32 v203, 0
	v_mov_b32_e32 v204, 0
	v_mov_b32_e32 v205, 0
	v_mov_b32_e32 v206, 0
	v_mov_b32_e32 v207, 0
	v_mov_b32_e32 v208, 0
	v_mov_b32_e32 v209, 0
	v_mov_b32_e32 v210, 0
	v_mov_b32_e32 v211, 0
	v_mov_b32_e32 v221, 0
	v_mov_b32_e32 v222, 0
	v_mov_b32_e32 v223, 0
	v_mov_b32_e32 v224, 0
	v_mov_b32_e32 v225, 0
	v_mov_b32_e32 v226, 0
	v_mov_b32_e32 v227, 0
	v_mov_b32_e32 v228, 0
	v_mov_b32_e32 v229, 0
	v_mov_b32_e32 v230, 0
	v_mov_b32_e32 v231, 0
	v_mov_b32_e32 v232, 0
	v_mov_b32_e32 v233, 0
	v_mov_b32_e32 v234, 0
	v_mov_b32_e32 v235, 0
	v_mov_b32_e32 v236, 0
	v_mov_b32_e32 v237, 0
	v_mov_b32_e32 v238, 0
	v_mov_b32_e32 v239, 0
	v_mov_b32_e32 v240, 0
	v_mov_b32_e32 v241, 0
	v_mov_b32_e32 v242, 0
	v_mov_b32_e32 v243, 0
	v_lshlrev_b32_e32 v0, 16, v8
	v_and_b32_e32 v1, s100, v8
	v_lshlrev_b32_e32 v172, 16, v9
	v_and_b32_e32 v173, s100, v9
	v_add_f32_e32 v214, v0, v175
	v_add_f32_e32 v215, v1, v176
	v_add_f32_e32 v216, v172, v177
	v_add_f32_e32 v217, v173, v178
	v_fma_f32 v244, v134, v179, v214
	v_fma_f32 v245, v134, v180, v215
	v_fma_f32 v246, v134, v181, v216
	v_fma_f32 v247, v134, v182, v217
	v_fma_f32 v249, v135, v187, v244
	v_fma_f32 v250, v135, v188, v245
	v_fma_f32 v251, v135, v189, v246
	v_fma_f32 v252, v135, v190, v247
	v_lshlrev_b32_e32 v253, 16, v12
	v_and_b32_e32 v254, s100, v12
	v_lshlrev_b32_e32 v255, 16, v13
	v_and_b32_e32 v179, s100, v13
	v_add_f32_e32 v180, v253, v0
	v_add_f32_e32 v181, v254, v1
	v_add_f32_e32 v182, v255, v172
	v_add_f32_e32 v187, v179, v173
	v_fma_f32 v188, v134, v183, v180
	v_fma_f32 v189, v134, v184, v181
	v_fma_f32 v190, v134, v185, v182
	v_fma_f32 v203, v134, v186, v187
	v_fma_f32 v204, v135, v191, v188
	v_fma_f32 v205, v135, v192, v189
	v_fma_f32 v206, v135, v193, v190
	v_fma_f32 v175, v135, v194, v203
	v_lshlrev_b32_e32 v176, 16, v16
	v_and_b32_e32 v177, s100, v16
	v_lshlrev_b32_e32 v178, 16, v17
	v_and_b32_e32 v183, s100, v17
	v_add_f32_e32 v184, v176, v253
	v_add_f32_e32 v185, v177, v254
	v_add_f32_e32 v186, v178, v255
	v_add_f32_e32 v191, v183, v179
	v_fma_f32 v192, v134, v214, v184
	v_fma_f32 v193, v134, v215, v185
	v_fma_f32 v194, v134, v216, v186
	v_fma_f32 v207, v134, v217, v191
	v_fma_f32 v208, v135, v195, v192
	v_fma_f32 v209, v135, v196, v193
	v_fma_f32 v210, v135, v197, v194
	v_fma_f32 v0, v135, v198, v207
	v_lshlrev_b32_e32 v1, 16, v20
	v_and_b32_e32 v172, s100, v20
	v_lshlrev_b32_e32 v173, 16, v21
	v_and_b32_e32 v214, s100, v21
	v_add_f32_e32 v215, v1, v176
	v_add_f32_e32 v216, v172, v177
	v_add_f32_e32 v217, v173, v178
	v_add_f32_e32 v195, v214, v183
	v_fma_f32 v196, v134, v180, v215
	v_fma_f32 v197, v134, v181, v216
	v_fma_f32 v198, v134, v182, v217
	v_fma_f32 v211, v134, v187, v195
	v_fma_f32 v221, v135, v199, v196
	v_fma_f32 v222, v135, v200, v197
	v_fma_f32 v223, v135, v201, v198
	v_fma_f32 v253, v135, v202, v211
	v_lshlrev_b32_e32 v254, 16, v24
	v_and_b32_e32 v255, s100, v24
	v_lshlrev_b32_e32 v179, 16, v25
	v_and_b32_e32 v180, s100, v25
	v_add_f32_e32 v181, v254, v1
	v_add_f32_e32 v182, v255, v172
	v_add_f32_e32 v187, v179, v173
	v_add_f32_e32 v199, v180, v214
	v_fma_f32 v200, v134, v184, v181
	v_fma_f32 v201, v134, v185, v182
	v_fma_f32 v202, v134, v186, v187
	v_fma_f32 v224, v134, v191, v199
	v_fma_f32 v225, v135, v244, v200
	v_fma_f32 v226, v135, v245, v201
	v_fma_f32 v227, v135, v246, v202
	v_fma_f32 v176, v135, v247, v224
	v_lshlrev_b32_e32 v177, 16, v28
	v_and_b32_e32 v178, s100, v28
	v_lshlrev_b32_e32 v183, 16, v29
	v_and_b32_e32 v184, s100, v29
	v_add_f32_e32 v185, v177, v254
	v_add_f32_e32 v186, v178, v255
	v_add_f32_e32 v191, v183, v179
	v_add_f32_e32 v244, v184, v180
	v_fma_f32 v245, v134, v215, v185
	v_fma_f32 v246, v134, v216, v186
	v_fma_f32 v247, v134, v217, v191
	v_fma_f32 v228, v134, v195, v244
	v_fma_f32 v229, v135, v188, v245
	v_fma_f32 v230, v135, v189, v246
	v_fma_f32 v231, v135, v190, v247
	v_fma_f32 v1, v135, v203, v228
	v_lshlrev_b32_e32 v172, 16, v32
	v_and_b32_e32 v173, s100, v32
	v_lshlrev_b32_e32 v214, 16, v33
	v_and_b32_e32 v215, s100, v33
	v_add_f32_e32 v216, v172, v177
	v_add_f32_e32 v217, v173, v178
	v_add_f32_e32 v195, v214, v183
	v_add_f32_e32 v188, v215, v184
	v_fma_f32 v189, v134, v181, v216
	v_fma_f32 v190, v134, v182, v217
	v_fma_f32 v203, v134, v187, v195
	v_fma_f32 v232, v134, v199, v188
	v_fma_f32 v233, v135, v192, v189
	v_fma_f32 v234, v135, v193, v190
	v_fma_f32 v235, v135, v194, v203
	v_fma_f32 v254, v135, v207, v232
	v_lshlrev_b32_e32 v255, 16, v36
; __device__ __forceinline__ unsigned pk2(float lo, float hi) { return pg8::cvt_pk_bf16(lo, hi); }
; __global__ void __launch_bounds__(NTHR, 2) hybrid_fwd(Args args) {
;     ...
;             float a[8];
; #pragma unroll
;             for (int e = 0; e < 8; ++e) a[e] = 0.f;
;             const u32x4 u0 = qv[0];
; #pragma unroll
;             for (int j = 0; j < 16; ++j) { const float mk = j < cnt ? 1.0f : 0.0f; const u32x4 q = qv[j];
;                 a[0] += mk * bflo(q.x); a[1] += mk * bfhi(q.x); a[2] += mk * bflo(q.y); a[3] += mk * bfhi(q.y); a[4] += mk * bflo(q.z); a[5] += mk * bfhi(q.z); a[6] += mk * bflo(q.w); a[7] += mk * bfhi(q.w); }
;             const float ic = 1.0f / (float)cnt;
;             u32x4 o; o.x = pk2(a[0] * ic - bflo(u0.x), a[1] * ic - bfhi(u0.x)); o.y = pk2(a[2] * ic - bflo(u0.y), a[3] * ic - bfhi(u0.y));
;             o.z = pk2(a[4] * ic - bflo(u0.z), a[5] * ic - bfhi(u0.z)); o.w = pk2(a[6] * ic - bflo(u0.w), a[7] * ic - bfhi(u0.w));
	v_and_b32_e32 v179, s100, v36
	v_lshlrev_b32_e32 v180, 16, v37
	v_and_b32_e32 v181, s100, v37
	v_add_f32_e32 v182, v255, v172
	v_add_f32_e32 v187, v179, v173
	v_add_f32_e32 v199, v180, v214
	v_add_f32_e32 v192, v181, v215
	v_fma_f32 v193, v134, v185, v182
	v_fma_f32 v194, v134, v186, v187
	v_fma_f32 v207, v134, v191, v199
	v_fma_f32 v236, v134, v244, v192
	v_fma_f32 v237, v135, v196, v193
	v_fma_f32 v238, v135, v197, v194
	v_fma_f32 v239, v135, v198, v207
	v_fma_f32 v177, v135, v211, v236
	v_lshlrev_b32_e32 v178, 16, v40
	v_and_b32_e32 v183, s100, v40
	v_lshlrev_b32_e32 v184, 16, v41
	v_and_b32_e32 v185, s100, v41
	v_add_f32_e32 v186, v178, v255
	v_add_f32_e32 v191, v183, v179
	v_add_f32_e32 v244, v184, v180
	v_add_f32_e32 v196, v185, v181
	v_fma_f32 v197, v134, v216, v186
	v_fma_f32 v198, v134, v217, v191
	v_fma_f32 v211, v134, v195, v244
	v_fma_f32 v240, v134, v188, v196
	v_fma_f32 v241, v135, v200, v197
	v_fma_f32 v242, v135, v201, v198
	v_fma_f32 v243, v135, v202, v211
	v_fma_f32 v172, v135, v224, v240
	v_lshlrev_b32_e32 v173, 16, v44
	v_and_b32_e32 v214, s100, v44
	v_lshlrev_b32_e32 v215, 16, v45
	v_and_b32_e32 v216, s100, v45
	v_add_f32_e32 v217, v173, v178
	v_add_f32_e32 v195, v214, v183
	v_add_f32_e32 v188, v215, v184
	v_add_f32_e32 v200, v216, v185
	v_fma_f32 v201, v134, v182, v217
	v_fma_f32 v202, v134, v187, v195
	v_fma_f32 v224, v134, v199, v188
	v_fma_f32 v249, v134, v192, v200
	v_fma_f32 v250, v135, v245, v201
	v_fma_f32 v251, v135, v246, v202
	v_fma_f32 v252, v135, v247, v224
	v_fma_f32 v255, v135, v228, v249
	v_lshlrev_b32_e32 v179, 16, v48
	v_and_b32_e32 v180, s100, v48
	v_lshlrev_b32_e32 v181, 16, v49
	v_and_b32_e32 v182, s100, v49
	v_add_f32_e32 v187, v179, v173
	v_add_f32_e32 v199, v180, v214
	v_add_f32_e32 v192, v181, v215
	v_add_f32_e32 v245, v182, v216
	v_fma_f32 v246, v134, v186, v187
	v_fma_f32 v247, v134, v191, v199
	v_fma_f32 v228, v134, v244, v192
	v_fma_f32 v204, v134, v196, v245
	v_fma_f32 v205, v135, v189, v246
	v_fma_f32 v206, v135, v190, v247
	v_fma_f32 v175, v135, v203, v228
	v_fma_f32 v178, v135, v232, v204
	v_lshlrev_b32_e32 v183, 16, v52
	v_and_b32_e32 v184, s100, v52
	v_lshlrev_b32_e32 v185, 16, v53
	v_and_b32_e32 v186, s100, v53
	v_add_f32_e32 v191, v183, v179
	v_add_f32_e32 v244, v184, v180
	v_add_f32_e32 v196, v185, v181
	v_add_f32_e32 v189, v186, v182
	v_fma_f32 v190, v134, v217, v191
	v_fma_f32 v203, v134, v195, v244
	v_fma_f32 v232, v134, v188, v196
	v_fma_f32 v208, v134, v200, v189
	v_fma_f32 v209, v135, v193, v190
	v_fma_f32 v210, v135, v194, v203
	v_fma_f32 v0, v135, v207, v232
	v_fma_f32 v173, v135, v236, v208
	v_lshlrev_b32_e32 v214, 16, v56
	v_and_b32_e32 v215, s100, v56
	v_lshlrev_b32_e32 v216, 16, v57
	v_and_b32_e32 v217, s100, v57
	v_add_f32_e32 v195, v214, v183
	v_add_f32_e32 v188, v215, v184
	v_add_f32_e32 v200, v216, v185
	v_add_f32_e32 v193, v217, v186
	v_fma_f32 v194, v134, v187, v195
	v_fma_f32 v207, v134, v199, v188
	v_fma_f32 v236, v134, v192, v200
	v_fma_f32 v221, v134, v245, v193
	v_fma_f32 v222, v135, v197, v194
	v_fma_f32 v223, v135, v198, v207
	v_fma_f32 v253, v135, v211, v236
	v_fma_f32 v179, v135, v240, v221
	v_lshlrev_b32_e32 v180, 16, v60
	v_and_b32_e32 v181, s100, v60
	v_lshlrev_b32_e32 v182, 16, v61
	v_and_b32_e32 v187, s100, v61
	v_add_f32_e32 v199, v180, v214
	v_add_f32_e32 v192, v181, v215
	v_add_f32_e32 v245, v182, v216
	v_add_f32_e32 v197, v187, v217
	v_fma_f32 v198, v134, v191, v199
	v_fma_f32 v211, v134, v244, v192
	v_fma_f32 v240, v134, v196, v245
	v_fma_f32 v225, v134, v189, v197
	v_fma_f32 v226, v135, v201, v198
	v_fma_f32 v227, v135, v202, v211
	v_fma_f32 v176, v135, v224, v240
	v_fma_f32 v183, v135, v249, v225
	v_lshlrev_b32_e32 v184, 16, v64
	v_and_b32_e32 v185, s100, v64
	v_lshlrev_b32_e32 v186, 16, v65
	v_and_b32_e32 v191, s100, v65
	v_add_f32_e32 v244, v184, v180
	v_add_f32_e32 v196, v185, v181
	v_add_f32_e32 v189, v186, v182
	v_add_f32_e32 v201, v191, v187
	v_fma_f32 v202, v134, v195, v244
	v_fma_f32 v224, v134, v188, v196
	v_fma_f32 v249, v134, v200, v189
	v_fma_f32 v229, v134, v193, v201
	v_fma_f32 v230, v135, v246, v202
	v_fma_f32 v231, v135, v247, v224
	v_fma_f32 v1, v135, v228, v249
	v_fma_f32 v214, v135, v204, v229
	v_lshlrev_b32_e32 v215, 16, v68
	v_and_b32_e32 v216, s100, v68
	v_lshlrev_b32_e32 v217, 16, v69
	v_and_b32_e32 v195, s100, v69
	v_add_f32_e32 v188, v215, v184
	v_add_f32_e32 v200, v216, v185
	v_add_f32_e32 v193, v217, v186
	v_add_f32_e32 v246, v195, v191
	v_fma_f32 v247, v134, v199, v188
	v_fma_f32 v228, v134, v192, v200
	v_fma_f32 v204, v134, v245, v193
	v_fma_f32 v233, v134, v197, v246
	v_fma_f32 v234, v135, v190, v247
	v_fma_f32 v235, v135, v203, v228
	v_fma_f32 v254, v135, v232, v204
	v_fma_f32 v180, v135, v208, v233
	v_fma_f32 v181, v136, v237, v234
	v_fma_f32 v182, v136, v238, v235
	v_fma_f32 v187, v136, v239, v254
	v_fma_f32 v199, v136, v177, v180
	s_add_i32 s101, s99, 1
	v_min_u32_e32 v192, s101, v137
	v_cvt_f32_u32_e32 v192, v192
	v_rcp_f32_e32 v192, v192
	s_nop 0
	v_fma_f32 v181, v181, v192, -v215
	v_fma_f32 v182, v182, v192, -v216
	v_fma_f32 v187, v187, v192, -v217
	v_fma_f32 v199, v199, v192, -v195
	v_cvt_pk_bf16_f32 v68, v181, v182
	v_cvt_pk_bf16_f32 v69, v187, v199
	v_lshlrev_b32_e32 v245, 16, v72
	v_and_b32_e32 v197, s100, v72
	v_lshlrev_b32_e32 v190, 16, v73
	v_and_b32_e32 v203, s100, v73
	v_add_f32_e32 v232, v245, v215
	v_add_f32_e32 v208, v197, v216
	v_add_f32_e32 v237, v190, v217
	v_add_f32_e32 v238, v203, v195
	v_fma_f32 v239, v134, v244, v232
	v_fma_f32 v177, v134, v196, v208
	v_fma_f32 v181, v134, v189, v237
	v_fma_f32 v182, v134, v201, v238
	v_fma_f32 v187, v135, v194, v239
	v_fma_f32 v199, v135, v207, v177
; __device__ __forceinline__ unsigned pk2(float lo, float hi) { return pg8::cvt_pk_bf16(lo, hi); }
; __global__ void __launch_bounds__(NTHR, 2) hybrid_fwd(Args args) {
;     ...
;             float a[8];
; #pragma unroll
;             for (int e = 0; e < 8; ++e) a[e] = 0.f;
;             const u32x4 u0 = qv[0];
; #pragma unroll
;             for (int j = 0; j < 16; ++j) { const float mk = j < cnt ? 1.0f : 0.0f; const u32x4 q = qv[j];
;                 a[0] += mk * bflo(q.x); a[1] += mk * bfhi(q.x); a[2] += mk * bflo(q.y); a[3] += mk * bfhi(q.y); a[4] += mk * bflo(q.z); a[5] += mk * bfhi(q.z); a[6] += mk * bflo(q.w); a[7] += mk * bfhi(q.w); }
;             const float ic = 1.0f / (float)cnt;
;             u32x4 o; o.x = pk2(a[0] * ic - bflo(u0.x), a[1] * ic - bfhi(u0.x)); o.y = pk2(a[2] * ic - bflo(u0.y), a[3] * ic - bfhi(u0.y));
;             o.z = pk2(a[4] * ic - bflo(u0.z), a[5] * ic - bfhi(u0.z)); o.w = pk2(a[6] * ic - bflo(u0.w), a[7] * ic - bfhi(u0.w));
	v_fma_f32 v192, v135, v236, v181
	v_fma_f32 v184, v135, v221, v182
	v_fma_f32 v185, v136, v241, v187
	v_fma_f32 v186, v136, v242, v199
	v_fma_f32 v191, v136, v243, v192
	v_fma_f32 v244, v136, v172, v184
	s_add_i32 s101, s99, 2
	v_min_u32_e32 v196, s101, v137
	v_cvt_f32_u32_e32 v196, v196
	v_rcp_f32_e32 v196, v196
	s_nop 0
	v_fma_f32 v185, v185, v196, -v245
	v_fma_f32 v186, v186, v196, -v197
	v_fma_f32 v191, v191, v196, -v190
	v_fma_f32 v244, v244, v196, -v203
	v_cvt_pk_bf16_f32 v72, v185, v186
	v_cvt_pk_bf16_f32 v73, v191, v244
	v_lshlrev_b32_e32 v189, 16, v76
	v_and_b32_e32 v201, s100, v76
	v_lshlrev_b32_e32 v194, 16, v77
	v_and_b32_e32 v207, s100, v77
	v_add_f32_e32 v236, v189, v245
	v_add_f32_e32 v221, v201, v197
	v_add_f32_e32 v241, v194, v190
	v_add_f32_e32 v242, v207, v203
	v_fma_f32 v243, v134, v188, v236
	v_fma_f32 v172, v134, v200, v221
	v_fma_f32 v185, v134, v193, v241
	v_fma_f32 v186, v134, v246, v242
	v_fma_f32 v191, v135, v198, v243
	v_fma_f32 v244, v135, v211, v172
	v_fma_f32 v196, v135, v240, v185
	v_fma_f32 v215, v135, v225, v186
	v_fma_f32 v216, v136, v250, v191
	v_fma_f32 v217, v136, v251, v244
	v_fma_f32 v195, v136, v252, v196
	v_fma_f32 v188, v136, v255, v215
	s_add_i32 s101, s99, 3
	v_min_u32_e32 v200, s101, v137
	v_cvt_f32_u32_e32 v200, v200
	v_rcp_f32_e32 v200, v200
	s_nop 0
	v_fma_f32 v216, v216, v200, -v189
	v_fma_f32 v217, v217, v200, -v201
	v_fma_f32 v195, v195, v200, -v194
	v_fma_f32 v188, v188, v200, -v207
	v_cvt_pk_bf16_f32 v76, v216, v217
	v_cvt_pk_bf16_f32 v77, v195, v188
	v_lshlrev_b32_e32 v193, 16, v80
	v_and_b32_e32 v246, s100, v80
	v_lshlrev_b32_e32 v198, 16, v81
	v_and_b32_e32 v211, s100, v81
	v_add_f32_e32 v240, v193, v189
	v_add_f32_e32 v225, v246, v201
	v_add_f32_e32 v250, v198, v194
	v_add_f32_e32 v251, v211, v207
	v_fma_f32 v252, v134, v232, v240
	v_fma_f32 v255, v134, v208, v225
	v_fma_f32 v216, v134, v237, v250
	v_fma_f32 v217, v134, v238, v251
	v_fma_f32 v195, v135, v202, v252
	v_fma_f32 v188, v135, v224, v255
	v_fma_f32 v200, v135, v249, v216
	v_fma_f32 v245, v135, v229, v217
	v_fma_f32 v197, v136, v205, v195
	v_fma_f32 v190, v136, v206, v188
	v_fma_f32 v203, v136, v175, v200
	v_fma_f32 v232, v136, v178, v245
	s_add_i32 s101, s99, 4
	v_min_u32_e32 v208, s101, v137
	v_cvt_f32_u32_e32 v208, v208
	v_rcp_f32_e32 v208, v208
	s_nop 0
	v_fma_f32 v197, v197, v208, -v193
	v_fma_f32 v190, v190, v208, -v246
	v_fma_f32 v203, v203, v208, -v198
	v_fma_f32 v232, v232, v208, -v211
	v_cvt_pk_bf16_f32 v80, v197, v190
	v_cvt_pk_bf16_f32 v81, v203, v232
	v_lshlrev_b32_e32 v237, 16, v84
	v_and_b32_e32 v238, s100, v84
	v_lshlrev_b32_e32 v202, 16, v85
	v_and_b32_e32 v224, s100, v85
	v_add_f32_e32 v249, v237, v193
	v_add_f32_e32 v229, v238, v246
	v_add_f32_e32 v205, v202, v198
	v_add_f32_e32 v206, v224, v211
	v_fma_f32 v175, v134, v236, v249
	v_fma_f32 v178, v134, v221, v229
	v_fma_f32 v197, v134, v241, v205
	v_fma_f32 v190, v134, v242, v206
	v_fma_f32 v203, v135, v247, v175
	v_fma_f32 v232, v135, v228, v178
	v_fma_f32 v208, v135, v204, v197
	v_fma_f32 v189, v135, v233, v190
	v_fma_f32 v201, v136, v209, v203
	v_fma_f32 v194, v136, v210, v232
	v_fma_f32 v207, v136, v0, v208
	v_fma_f32 v236, v136, v173, v189
	s_add_i32 s101, s99, 5
	v_min_u32_e32 v221, s101, v137
	v_cvt_f32_u32_e32 v221, v221
	v_rcp_f32_e32 v221, v221
	s_nop 0
	v_fma_f32 v201, v201, v221, -v237
	v_fma_f32 v194, v194, v221, -v238
	v_fma_f32 v207, v207, v221, -v202
	v_fma_f32 v236, v236, v221, -v224
	v_cvt_pk_bf16_f32 v84, v201, v194
	v_cvt_pk_bf16_f32 v85, v207, v236
	v_lshlrev_b32_e32 v241, 16, v88
	v_and_b32_e32 v242, s100, v88
	v_lshlrev_b32_e32 v247, 16, v89
	v_and_b32_e32 v228, s100, v89
	v_add_f32_e32 v204, v241, v237
	v_add_f32_e32 v233, v242, v238
	v_add_f32_e32 v209, v247, v202
	v_add_f32_e32 v210, v228, v224
	v_fma_f32 v0, v134, v240, v204
	v_fma_f32 v173, v134, v225, v233
	v_fma_f32 v201, v134, v250, v209
	v_fma_f32 v194, v134, v251, v210
	v_fma_f32 v207, v135, v239, v0
	v_fma_f32 v236, v135, v177, v173
	v_fma_f32 v221, v135, v181, v201
	v_fma_f32 v193, v135, v182, v194
	v_fma_f32 v246, v136, v222, v207
	v_fma_f32 v198, v136, v223, v236
	v_fma_f32 v211, v136, v253, v221
	v_fma_f32 v240, v136, v179, v193
	s_add_i32 s101, s99, 6
	v_min_u32_e32 v225, s101, v137
	v_cvt_f32_u32_e32 v225, v225
	v_rcp_f32_e32 v225, v225
	s_nop 0
	v_fma_f32 v246, v246, v225, -v241
	v_fma_f32 v198, v198, v225, -v242
	v_fma_f32 v211, v211, v225, -v247
	v_fma_f32 v240, v240, v225, -v228
	v_cvt_pk_bf16_f32 v88, v246, v198
	v_cvt_pk_bf16_f32 v89, v211, v240
	v_lshlrev_b32_e32 v250, 16, v92
	v_and_b32_e32 v251, s100, v92
	v_lshlrev_b32_e32 v239, 16, v93
	v_and_b32_e32 v177, s100, v93
	v_add_f32_e32 v181, v250, v241
	v_add_f32_e32 v182, v251, v242
	v_add_f32_e32 v222, v239, v247
	v_add_f32_e32 v223, v177, v228
	v_fma_f32 v253, v134, v249, v181
	v_fma_f32 v179, v134, v229, v182
	v_fma_f32 v246, v134, v205, v222
	v_fma_f32 v198, v134, v206, v223
	v_fma_f32 v211, v135, v243, v253
	v_fma_f32 v240, v135, v172, v179
	v_fma_f32 v225, v135, v185, v246
	v_fma_f32 v237, v135, v186, v198
	v_fma_f32 v238, v136, v226, v211
	v_fma_f32 v202, v136, v227, v240
	v_fma_f32 v224, v136, v176, v225
	v_fma_f32 v249, v136, v183, v237
	s_add_i32 s101, s99, 7
	v_min_u32_e32 v229, s101, v137
	v_cvt_f32_u32_e32 v229, v229
	v_rcp_f32_e32 v229, v229
	s_nop 0
	v_fma_f32 v238, v238, v229, -v250
	v_fma_f32 v202, v202, v229, -v251
	v_fma_f32 v224, v224, v229, -v239
	v_fma_f32 v249, v249, v229, -v177
	v_cvt_pk_bf16_f32 v92, v238, v202
	v_cvt_pk_bf16_f32 v93, v224, v249
	v_lshlrev_b32_e32 v205, 16, v96
	v_and_b32_e32 v206, s100, v96
	v_lshlrev_b32_e32 v243, 16, v97
	v_and_b32_e32 v172, s100, v97
; __device__ __forceinline__ unsigned pk2(float lo, float hi) { return pg8::cvt_pk_bf16(lo, hi); }
; __global__ void __launch_bounds__(NTHR, 2) hybrid_fwd(Args args) {
;     ...
;             float a[8];
; #pragma unroll
;             for (int e = 0; e < 8; ++e) a[e] = 0.f;
;             const u32x4 u0 = qv[0];
; #pragma unroll
;             for (int j = 0; j < 16; ++j) { const float mk = j < cnt ? 1.0f : 0.0f; const u32x4 q = qv[j];
;                 a[0] += mk * bflo(q.x); a[1] += mk * bfhi(q.x); a[2] += mk * bflo(q.y); a[3] += mk * bfhi(q.y); a[4] += mk * bflo(q.z); a[5] += mk * bfhi(q.z); a[6] += mk * bflo(q.w); a[7] += mk * bfhi(q.w); }
;             const float ic = 1.0f / (float)cnt;
;             u32x4 o; o.x = pk2(a[0] * ic - bflo(u0.x), a[1] * ic - bfhi(u0.x)); o.y = pk2(a[2] * ic - bflo(u0.y), a[3] * ic - bfhi(u0.y));
;             o.z = pk2(a[4] * ic - bflo(u0.z), a[5] * ic - bfhi(u0.z)); o.w = pk2(a[6] * ic - bflo(u0.w), a[7] * ic - bfhi(u0.w));
	v_add_f32_e32 v185, v205, v250
	v_add_f32_e32 v186, v206, v251
	v_add_f32_e32 v226, v243, v239
	v_add_f32_e32 v227, v172, v177
	v_fma_f32 v176, v134, v204, v185
	v_fma_f32 v183, v134, v233, v186
	v_fma_f32 v238, v134, v209, v226
	v_fma_f32 v202, v134, v210, v227
	v_fma_f32 v224, v135, v252, v176
	v_fma_f32 v249, v135, v255, v183
	v_fma_f32 v229, v135, v216, v238
	v_fma_f32 v241, v135, v217, v202
	v_fma_f32 v242, v136, v230, v224
	v_fma_f32 v247, v136, v231, v249
	v_fma_f32 v228, v136, v1, v229
	v_fma_f32 v204, v136, v214, v241
	s_add_i32 s101, s99, 8
	v_min_u32_e32 v233, s101, v137
	v_cvt_f32_u32_e32 v233, v233
	v_rcp_f32_e32 v233, v233
	s_nop 0
	v_fma_f32 v242, v242, v233, -v205
	v_fma_f32 v247, v247, v233, -v206
	v_fma_f32 v228, v228, v233, -v243
	v_fma_f32 v204, v204, v233, -v172
	v_cvt_pk_bf16_f32 v96, v242, v247
	v_cvt_pk_bf16_f32 v97, v228, v204
	v_lshlrev_b32_e32 v209, 16, v100
	v_and_b32_e32 v210, s100, v100
	v_lshlrev_b32_e32 v252, 16, v101
	v_and_b32_e32 v255, s100, v101
	v_add_f32_e32 v216, v209, v205
	v_add_f32_e32 v217, v210, v206
	v_add_f32_e32 v230, v252, v243
	v_add_f32_e32 v231, v255, v172
	v_fma_f32 v1, v134, v181, v216
	v_fma_f32 v214, v134, v182, v217
	v_fma_f32 v242, v134, v222, v230
	v_fma_f32 v247, v134, v223, v231
	v_fma_f32 v228, v135, v175, v1
	v_fma_f32 v204, v135, v178, v214
	v_fma_f32 v233, v135, v197, v242
	v_fma_f32 v250, v135, v190, v247
	v_fma_f32 v251, v136, v234, v228
	v_fma_f32 v239, v136, v235, v204
	v_fma_f32 v177, v136, v254, v233
	v_fma_f32 v181, v136, v180, v250
	s_add_i32 s101, s99, 9
	v_min_u32_e32 v182, s101, v137
	v_cvt_f32_u32_e32 v182, v182
	v_rcp_f32_e32 v182, v182
	s_nop 0
	v_fma_f32 v251, v251, v182, -v209
	v_fma_f32 v239, v239, v182, -v210
	v_fma_f32 v177, v177, v182, -v252
	v_fma_f32 v181, v181, v182, -v255
	v_cvt_pk_bf16_f32 v100, v251, v239
	v_cvt_pk_bf16_f32 v101, v177, v181
	v_lshlrev_b32_e32 v222, 16, v104
	v_and_b32_e32 v223, s100, v104
	v_lshlrev_b32_e32 v175, 16, v105
	v_and_b32_e32 v178, s100, v105
	v_add_f32_e32 v197, v222, v209
	v_add_f32_e32 v190, v223, v210
	v_add_f32_e32 v234, v175, v252
	v_add_f32_e32 v235, v178, v255
	v_fma_f32 v254, v134, v185, v197
	v_fma_f32 v180, v134, v186, v190
	v_fma_f32 v251, v134, v226, v234
	v_fma_f32 v239, v134, v227, v235
	v_fma_f32 v177, v135, v0, v254
	v_fma_f32 v181, v135, v173, v180
	v_fma_f32 v182, v135, v201, v251
	v_fma_f32 v205, v135, v194, v239
	v_fma_f32 v206, v136, v187, v177
	v_fma_f32 v243, v136, v199, v181
	v_fma_f32 v172, v136, v192, v182
	v_fma_f32 v185, v136, v184, v205
	s_add_i32 s101, s99, 10
	v_min_u32_e32 v186, s101, v137
	v_cvt_f32_u32_e32 v186, v186
	v_rcp_f32_e32 v186, v186
	s_nop 0
	v_fma_f32 v206, v206, v186, -v222
	v_fma_f32 v243, v243, v186, -v223
	v_fma_f32 v172, v172, v186, -v175
	v_fma_f32 v185, v185, v186, -v178
	v_cvt_pk_bf16_f32 v104, v206, v243
	v_cvt_pk_bf16_f32 v105, v172, v185
	v_lshlrev_b32_e32 v226, 16, v108
	v_and_b32_e32 v227, s100, v108
	v_lshlrev_b32_e32 v0, 16, v109
	v_and_b32_e32 v173, s100, v109
	v_add_f32_e32 v201, v226, v222
	v_add_f32_e32 v194, v227, v223
	v_add_f32_e32 v187, v0, v175
	v_add_f32_e32 v199, v173, v178
	v_fma_f32 v192, v134, v216, v201
	v_fma_f32 v184, v134, v217, v194
	v_fma_f32 v206, v134, v230, v187
	v_fma_f32 v243, v134, v231, v199
	v_fma_f32 v172, v135, v253, v192
	v_fma_f32 v185, v135, v179, v184
	v_fma_f32 v186, v135, v246, v206
	v_fma_f32 v209, v135, v198, v243
	v_fma_f32 v210, v136, v191, v172
	v_fma_f32 v252, v136, v244, v185
	v_fma_f32 v255, v136, v196, v186
	v_fma_f32 v216, v136, v215, v209
	s_add_i32 s101, s99, 11
	v_min_u32_e32 v217, s101, v137
	v_cvt_f32_u32_e32 v217, v217
	v_rcp_f32_e32 v217, v217
	s_nop 0
	v_fma_f32 v210, v210, v217, -v226
	v_fma_f32 v252, v252, v217, -v227
	v_fma_f32 v255, v255, v217, -v0
	v_fma_f32 v216, v216, v217, -v173
	v_cvt_pk_bf16_f32 v108, v210, v252
	v_cvt_pk_bf16_f32 v109, v255, v216
	v_lshlrev_b32_e32 v230, 16, v112
	v_and_b32_e32 v231, s100, v112
	v_lshlrev_b32_e32 v253, 16, v113
	v_and_b32_e32 v179, s100, v113
	v_add_f32_e32 v246, v230, v226
	v_add_f32_e32 v198, v231, v227
	v_add_f32_e32 v191, v253, v0
	v_add_f32_e32 v244, v179, v173
	v_fma_f32 v196, v134, v197, v246
	v_fma_f32 v215, v134, v190, v198
	v_fma_f32 v210, v134, v234, v191
	v_fma_f32 v252, v134, v235, v244
	v_fma_f32 v255, v135, v176, v196
	v_fma_f32 v216, v135, v183, v215
	v_fma_f32 v217, v135, v238, v210
	v_fma_f32 v222, v135, v202, v252
	v_fma_f32 v223, v136, v195, v255
	v_fma_f32 v175, v136, v188, v216
	v_fma_f32 v178, v136, v200, v217
	v_fma_f32 v197, v136, v245, v222
	s_add_i32 s101, s99, 12
	v_min_u32_e32 v190, s101, v137
	v_cvt_f32_u32_e32 v190, v190
	v_rcp_f32_e32 v190, v190
	s_nop 0
	v_fma_f32 v223, v223, v190, -v230
	v_fma_f32 v175, v175, v190, -v231
	v_fma_f32 v178, v178, v190, -v253
	v_fma_f32 v197, v197, v190, -v179
	v_cvt_pk_bf16_f32 v112, v223, v175
	v_cvt_pk_bf16_f32 v113, v178, v197
	v_lshlrev_b32_e32 v234, 16, v116
	v_and_b32_e32 v235, s100, v116
	v_lshlrev_b32_e32 v176, 16, v117
	v_and_b32_e32 v183, s100, v117
	v_add_f32_e32 v238, v234, v230
	v_add_f32_e32 v202, v235, v231
	v_add_f32_e32 v195, v176, v253
	v_add_f32_e32 v188, v183, v179
	v_fma_f32 v200, v134, v201, v238
	v_fma_f32 v245, v134, v194, v202
	v_fma_f32 v223, v134, v187, v195
	v_fma_f32 v175, v134, v199, v188
	v_fma_f32 v178, v135, v1, v200
	v_fma_f32 v197, v135, v214, v245
	v_fma_f32 v190, v135, v242, v223
	v_fma_f32 v226, v135, v247, v175
	v_fma_f32 v227, v136, v203, v178
	v_fma_f32 v0, v136, v232, v197
	v_fma_f32 v173, v136, v208, v190
	v_fma_f32 v201, v136, v189, v226
	s_add_i32 s101, s99, 13
	v_min_u32_e32 v194, s101, v137
	v_cvt_f32_u32_e32 v194, v194
	v_rcp_f32_e32 v194, v194
	s_nop 0
; __device__ __forceinline__ unsigned pk2(float lo, float hi) { return pg8::cvt_pk_bf16(lo, hi); }
; __global__ void __launch_bounds__(NTHR, 2) hybrid_fwd(Args args) {
;     ...
;             float a[8];
; #pragma unroll
;             for (int e = 0; e < 8; ++e) a[e] = 0.f;
;             const u32x4 u0 = qv[0];
; #pragma unroll
;             for (int j = 0; j < 16; ++j) { const float mk = j < cnt ? 1.0f : 0.0f; const u32x4 q = qv[j];
;                 a[0] += mk * bflo(q.x); a[1] += mk * bfhi(q.x); a[2] += mk * bflo(q.y); a[3] += mk * bfhi(q.y); a[4] += mk * bflo(q.z); a[5] += mk * bfhi(q.z); a[6] += mk * bflo(q.w); a[7] += mk * bfhi(q.w); }
;             const float ic = 1.0f / (float)cnt;
;             u32x4 o; o.x = pk2(a[0] * ic - bflo(u0.x), a[1] * ic - bfhi(u0.x)); o.y = pk2(a[2] * ic - bflo(u0.y), a[3] * ic - bfhi(u0.y));
;             o.z = pk2(a[4] * ic - bflo(u0.z), a[5] * ic - bfhi(u0.z)); o.w = pk2(a[6] * ic - bflo(u0.w), a[7] * ic - bfhi(u0.w));
	v_fma_f32 v227, v227, v194, -v234
	v_fma_f32 v0, v0, v194, -v235
	v_fma_f32 v173, v173, v194, -v176
	v_fma_f32 v201, v201, v194, -v183
	v_cvt_pk_bf16_f32 v116, v227, v0
	v_cvt_pk_bf16_f32 v117, v173, v201
	v_lshlrev_b32_e32 v187, 16, v120
	v_and_b32_e32 v199, s100, v120
	v_lshlrev_b32_e32 v1, 16, v121
	v_and_b32_e32 v214, s100, v121
	v_add_f32_e32 v242, v187, v234
	v_add_f32_e32 v247, v199, v235
	v_add_f32_e32 v203, v1, v176
	v_add_f32_e32 v232, v214, v183
	v_fma_f32 v208, v134, v246, v242
	v_fma_f32 v189, v134, v198, v247
	v_fma_f32 v227, v134, v191, v203
	v_fma_f32 v0, v134, v244, v232
	v_fma_f32 v173, v135, v254, v208
	v_fma_f32 v201, v135, v180, v189
	v_fma_f32 v194, v135, v251, v227
	v_fma_f32 v230, v135, v239, v0
	v_fma_f32 v231, v136, v207, v173
	v_fma_f32 v253, v136, v236, v201
	v_fma_f32 v179, v136, v221, v194
	v_fma_f32 v246, v136, v193, v230
	s_add_i32 s101, s99, 14
	v_min_u32_e32 v198, s101, v137
	v_cvt_f32_u32_e32 v198, v198
	v_rcp_f32_e32 v198, v198
	s_nop 0
	v_fma_f32 v231, v231, v198, -v187
	v_fma_f32 v253, v253, v198, -v199
	v_fma_f32 v179, v179, v198, -v1
	v_fma_f32 v246, v246, v198, -v214
	v_cvt_pk_bf16_f32 v120, v231, v253
	v_cvt_pk_bf16_f32 v121, v179, v246
	v_lshlrev_b32_e32 v191, 16, v124
	v_and_b32_e32 v244, s100, v124
	v_lshlrev_b32_e32 v254, 16, v125
	v_and_b32_e32 v180, s100, v125
	v_add_f32_e32 v251, v191, v187
	v_add_f32_e32 v239, v244, v199
	v_add_f32_e32 v207, v254, v1
	v_add_f32_e32 v236, v180, v214
	v_fma_f32 v221, v134, v238, v251
	v_fma_f32 v193, v134, v202, v239
	v_fma_f32 v231, v134, v195, v207
	v_fma_f32 v253, v134, v188, v236
	v_fma_f32 v179, v135, v192, v221
	v_fma_f32 v246, v135, v184, v193
	v_fma_f32 v198, v135, v206, v231
	v_fma_f32 v234, v135, v243, v253
	v_fma_f32 v235, v136, v211, v179
	v_fma_f32 v176, v136, v240, v246
	v_fma_f32 v183, v136, v225, v198
	v_fma_f32 v238, v136, v237, v234
	s_add_i32 s101, s99, 15
	v_min_u32_e32 v202, s101, v137
	v_cvt_f32_u32_e32 v202, v202
	v_rcp_f32_e32 v202, v202
	s_nop 0
	v_fma_f32 v235, v235, v202, -v191
	v_fma_f32 v176, v176, v202, -v244
	v_fma_f32 v183, v183, v202, -v254
	v_fma_f32 v238, v238, v202, -v180
	v_cvt_pk_bf16_f32 v124, v235, v176
	v_cvt_pk_bf16_f32 v125, v183, v238
	v_lshlrev_b32_e32 v195, 16, v128
	v_and_b32_e32 v188, s100, v128
	v_lshlrev_b32_e32 v192, 16, v129
	v_and_b32_e32 v184, s100, v129
	v_add_f32_e32 v206, v195, v191
	v_add_f32_e32 v243, v188, v244
	v_add_f32_e32 v211, v192, v254
	v_add_f32_e32 v240, v184, v180
	v_fma_f32 v225, v134, v242, v206
	v_fma_f32 v237, v134, v247, v243
	v_fma_f32 v235, v134, v203, v211
	v_fma_f32 v176, v134, v232, v240
	v_fma_f32 v183, v135, v196, v225
	v_fma_f32 v238, v135, v215, v237
	v_fma_f32 v202, v135, v210, v235
	v_fma_f32 v187, v135, v252, v176
	v_fma_f32 v199, v136, v224, v183
	v_fma_f32 v1, v136, v249, v238
	v_fma_f32 v214, v136, v229, v202
	v_fma_f32 v242, v136, v241, v187
	s_add_i32 s101, s99, 16
	v_min_u32_e32 v247, s101, v137
	v_cvt_f32_u32_e32 v247, v247
	v_rcp_f32_e32 v247, v247
	s_nop 0
	v_fma_f32 v199, v199, v247, -v195
	v_fma_f32 v1, v1, v247, -v188
	v_fma_f32 v214, v214, v247, -v192
	v_fma_f32 v242, v242, v247, -v184
	v_cvt_pk_bf16_f32 v128, v199, v1
	v_cvt_pk_bf16_f32 v129, v214, v242
	v_mov_b32_e32 v175, 0
	v_mov_b32_e32 v176, 0
	v_mov_b32_e32 v177, 0
	v_mov_b32_e32 v178, 0
	v_mov_b32_e32 v179, 0
	v_mov_b32_e32 v180, 0
	v_mov_b32_e32 v181, 0
	v_mov_b32_e32 v182, 0
	v_mov_b32_e32 v183, 0
	v_mov_b32_e32 v184, 0
	v_mov_b32_e32 v185, 0
	v_mov_b32_e32 v186, 0
	v_mov_b32_e32 v187, 0
	v_mov_b32_e32 v188, 0
	v_mov_b32_e32 v189, 0
	v_mov_b32_e32 v190, 0
	v_mov_b32_e32 v191, 0
	v_mov_b32_e32 v192, 0
	v_mov_b32_e32 v193, 0
	v_mov_b32_e32 v194, 0
	v_mov_b32_e32 v195, 0
	v_mov_b32_e32 v196, 0
	v_mov_b32_e32 v197, 0
	v_mov_b32_e32 v198, 0
	v_mov_b32_e32 v199, 0
	v_mov_b32_e32 v200, 0
	v_mov_b32_e32 v201, 0
	v_mov_b32_e32 v202, 0
	v_mov_b32_e32 v203, 0
	v_mov_b32_e32 v204, 0
	v_mov_b32_e32 v205, 0
	v_mov_b32_e32 v206, 0
	v_mov_b32_e32 v207, 0
	v_mov_b32_e32 v208, 0
	v_mov_b32_e32 v209, 0
	v_mov_b32_e32 v210, 0
	v_mov_b32_e32 v211, 0
	v_mov_b32_e32 v221, 0
	v_mov_b32_e32 v222, 0
	v_mov_b32_e32 v223, 0
	v_mov_b32_e32 v224, 0
	v_mov_b32_e32 v225, 0
	v_mov_b32_e32 v226, 0
	v_mov_b32_e32 v227, 0
	v_mov_b32_e32 v228, 0
	v_mov_b32_e32 v229, 0
	v_mov_b32_e32 v230, 0
	v_mov_b32_e32 v231, 0
	v_mov_b32_e32 v232, 0
	v_mov_b32_e32 v233, 0
	v_mov_b32_e32 v234, 0
	v_mov_b32_e32 v235, 0
	v_mov_b32_e32 v236, 0
	v_mov_b32_e32 v237, 0
	v_mov_b32_e32 v238, 0
	v_mov_b32_e32 v239, 0
	v_mov_b32_e32 v240, 0
	v_mov_b32_e32 v241, 0
	v_mov_b32_e32 v242, 0
	v_mov_b32_e32 v243, 0
	v_lshlrev_b32_e32 v0, 16, v10
	v_and_b32_e32 v1, s100, v10
	v_lshlrev_b32_e32 v172, 16, v11
	v_and_b32_e32 v173, s100, v11
	v_add_f32_e32 v214, v0, v175
	v_add_f32_e32 v215, v1, v176
	v_add_f32_e32 v216, v172, v177
	v_add_f32_e32 v217, v173, v178
	v_fma_f32 v244, v134, v179, v214
	v_fma_f32 v245, v134, v180, v215
	v_fma_f32 v246, v134, v181, v216
	v_fma_f32 v247, v134, v182, v217
	v_fma_f32 v249, v135, v187, v244
	v_fma_f32 v250, v135, v188, v245
	v_fma_f32 v251, v135, v189, v246
	v_fma_f32 v252, v135, v190, v247
	v_lshlrev_b32_e32 v253, 16, v14
	v_and_b32_e32 v254, s100, v14
	v_lshlrev_b32_e32 v255, 16, v15
	v_and_b32_e32 v179, s100, v15
	v_add_f32_e32 v180, v253, v0
	v_add_f32_e32 v181, v254, v1
	v_add_f32_e32 v182, v255, v172
	v_add_f32_e32 v187, v179, v173
	v_fma_f32 v188, v134, v183, v180
	v_fma_f32 v189, v134, v184, v181
	v_fma_f32 v190, v134, v185, v182
	v_fma_f32 v203, v134, v186, v187
	v_fma_f32 v204, v135, v191, v188
	v_fma_f32 v205, v135, v192, v189
	v_fma_f32 v206, v135, v193, v190
	v_fma_f32 v175, v135, v194, v203
	v_lshlrev_b32_e32 v176, 16, v18
; __device__ __forceinline__ unsigned pk2(float lo, float hi) { return pg8::cvt_pk_bf16(lo, hi); }
; __global__ void __launch_bounds__(NTHR, 2) hybrid_fwd(Args args) {
;     ...
;             float a[8];
; #pragma unroll
;             for (int e = 0; e < 8; ++e) a[e] = 0.f;
;             const u32x4 u0 = qv[0];
; #pragma unroll
;             for (int j = 0; j < 16; ++j) { const float mk = j < cnt ? 1.0f : 0.0f; const u32x4 q = qv[j];
;                 a[0] += mk * bflo(q.x); a[1] += mk * bfhi(q.x); a[2] += mk * bflo(q.y); a[3] += mk * bfhi(q.y); a[4] += mk * bflo(q.z); a[5] += mk * bfhi(q.z); a[6] += mk * bflo(q.w); a[7] += mk * bfhi(q.w); }
;             const float ic = 1.0f / (float)cnt;
;             u32x4 o; o.x = pk2(a[0] * ic - bflo(u0.x), a[1] * ic - bfhi(u0.x)); o.y = pk2(a[2] * ic - bflo(u0.y), a[3] * ic - bfhi(u0.y));
;             o.z = pk2(a[4] * ic - bflo(u0.z), a[5] * ic - bfhi(u0.z)); o.w = pk2(a[6] * ic - bflo(u0.w), a[7] * ic - bfhi(u0.w));
	v_and_b32_e32 v177, s100, v18
	v_lshlrev_b32_e32 v178, 16, v19
	v_and_b32_e32 v183, s100, v19
	v_add_f32_e32 v184, v176, v253
	v_add_f32_e32 v185, v177, v254
	v_add_f32_e32 v186, v178, v255
	v_add_f32_e32 v191, v183, v179
	v_fma_f32 v192, v134, v214, v184
	v_fma_f32 v193, v134, v215, v185
	v_fma_f32 v194, v134, v216, v186
	v_fma_f32 v207, v134, v217, v191
	v_fma_f32 v208, v135, v195, v192
	v_fma_f32 v209, v135, v196, v193
	v_fma_f32 v210, v135, v197, v194
	v_fma_f32 v0, v135, v198, v207
	v_lshlrev_b32_e32 v1, 16, v22
	v_and_b32_e32 v172, s100, v22
	v_lshlrev_b32_e32 v173, 16, v23
	v_and_b32_e32 v214, s100, v23
	v_add_f32_e32 v215, v1, v176
	v_add_f32_e32 v216, v172, v177
	v_add_f32_e32 v217, v173, v178
	v_add_f32_e32 v195, v214, v183
	v_fma_f32 v196, v134, v180, v215
	v_fma_f32 v197, v134, v181, v216
	v_fma_f32 v198, v134, v182, v217
	v_fma_f32 v211, v134, v187, v195
	v_fma_f32 v221, v135, v199, v196
	v_fma_f32 v222, v135, v200, v197
	v_fma_f32 v223, v135, v201, v198
	v_fma_f32 v253, v135, v202, v211
	v_lshlrev_b32_e32 v254, 16, v26
	v_and_b32_e32 v255, s100, v26
	v_lshlrev_b32_e32 v179, 16, v27
	v_and_b32_e32 v180, s100, v27
	v_add_f32_e32 v181, v254, v1
	v_add_f32_e32 v182, v255, v172
	v_add_f32_e32 v187, v179, v173
	v_add_f32_e32 v199, v180, v214
	v_fma_f32 v200, v134, v184, v181
	v_fma_f32 v201, v134, v185, v182
	v_fma_f32 v202, v134, v186, v187
	v_fma_f32 v224, v134, v191, v199
	v_fma_f32 v225, v135, v244, v200
	v_fma_f32 v226, v135, v245, v201
	v_fma_f32 v227, v135, v246, v202
	v_fma_f32 v176, v135, v247, v224
	v_lshlrev_b32_e32 v177, 16, v30
	v_and_b32_e32 v178, s100, v30
	v_lshlrev_b32_e32 v183, 16, v31
	v_and_b32_e32 v184, s100, v31
	v_add_f32_e32 v185, v177, v254
	v_add_f32_e32 v186, v178, v255
	v_add_f32_e32 v191, v183, v179
	v_add_f32_e32 v244, v184, v180
	v_fma_f32 v245, v134, v215, v185
	v_fma_f32 v246, v134, v216, v186
	v_fma_f32 v247, v134, v217, v191
	v_fma_f32 v228, v134, v195, v244
	v_fma_f32 v229, v135, v188, v245
	v_fma_f32 v230, v135, v189, v246
	v_fma_f32 v231, v135, v190, v247
	v_fma_f32 v1, v135, v203, v228
	v_lshlrev_b32_e32 v172, 16, v34
	v_and_b32_e32 v173, s100, v34
	v_lshlrev_b32_e32 v214, 16, v35
	v_and_b32_e32 v215, s100, v35
	v_add_f32_e32 v216, v172, v177
	v_add_f32_e32 v217, v173, v178
	v_add_f32_e32 v195, v214, v183
	v_add_f32_e32 v188, v215, v184
	v_fma_f32 v189, v134, v181, v216
	v_fma_f32 v190, v134, v182, v217
	v_fma_f32 v203, v134, v187, v195
	v_fma_f32 v232, v134, v199, v188
	v_fma_f32 v233, v135, v192, v189
	v_fma_f32 v234, v135, v193, v190
	v_fma_f32 v235, v135, v194, v203
	v_fma_f32 v254, v135, v207, v232
	v_lshlrev_b32_e32 v255, 16, v38
	v_and_b32_e32 v179, s100, v38
	v_lshlrev_b32_e32 v180, 16, v39
	v_and_b32_e32 v181, s100, v39
	v_add_f32_e32 v182, v255, v172
	v_add_f32_e32 v187, v179, v173
	v_add_f32_e32 v199, v180, v214
	v_add_f32_e32 v192, v181, v215
	v_fma_f32 v193, v134, v185, v182
	v_fma_f32 v194, v134, v186, v187
	v_fma_f32 v207, v134, v191, v199
	v_fma_f32 v236, v134, v244, v192
	v_fma_f32 v237, v135, v196, v193
	v_fma_f32 v238, v135, v197, v194
	v_fma_f32 v239, v135, v198, v207
	v_fma_f32 v177, v135, v211, v236
	v_lshlrev_b32_e32 v178, 16, v42
	v_and_b32_e32 v183, s100, v42
	v_lshlrev_b32_e32 v184, 16, v43
	v_and_b32_e32 v185, s100, v43
	v_add_f32_e32 v186, v178, v255
	v_add_f32_e32 v191, v183, v179
	v_add_f32_e32 v244, v184, v180
	v_add_f32_e32 v196, v185, v181
	v_fma_f32 v197, v134, v216, v186
	v_fma_f32 v198, v134, v217, v191
	v_fma_f32 v211, v134, v195, v244
	v_fma_f32 v240, v134, v188, v196
	v_fma_f32 v241, v135, v200, v197
	v_fma_f32 v242, v135, v201, v198
	v_fma_f32 v243, v135, v202, v211
	v_fma_f32 v172, v135, v224, v240
	v_lshlrev_b32_e32 v173, 16, v46
	v_and_b32_e32 v214, s100, v46
	v_lshlrev_b32_e32 v215, 16, v47
	v_and_b32_e32 v216, s100, v47
	v_add_f32_e32 v217, v173, v178
	v_add_f32_e32 v195, v214, v183
	v_add_f32_e32 v188, v215, v184
	v_add_f32_e32 v200, v216, v185
	v_fma_f32 v201, v134, v182, v217
	v_fma_f32 v202, v134, v187, v195
	v_fma_f32 v224, v134, v199, v188
	v_fma_f32 v249, v134, v192, v200
	v_fma_f32 v250, v135, v245, v201
	v_fma_f32 v251, v135, v246, v202
	v_fma_f32 v252, v135, v247, v224
	v_fma_f32 v255, v135, v228, v249
	v_lshlrev_b32_e32 v179, 16, v50
	v_and_b32_e32 v180, s100, v50
	v_lshlrev_b32_e32 v181, 16, v51
	v_and_b32_e32 v182, s100, v51
	v_add_f32_e32 v187, v179, v173
	v_add_f32_e32 v199, v180, v214
	v_add_f32_e32 v192, v181, v215
	v_add_f32_e32 v245, v182, v216
	v_fma_f32 v246, v134, v186, v187
	v_fma_f32 v247, v134, v191, v199
	v_fma_f32 v228, v134, v244, v192
	v_fma_f32 v204, v134, v196, v245
	v_fma_f32 v205, v135, v189, v246
	v_fma_f32 v206, v135, v190, v247
	v_fma_f32 v175, v135, v203, v228
	v_fma_f32 v178, v135, v232, v204
	v_lshlrev_b32_e32 v183, 16, v54
	v_and_b32_e32 v184, s100, v54
	v_lshlrev_b32_e32 v185, 16, v55
	v_and_b32_e32 v186, s100, v55
	v_add_f32_e32 v191, v183, v179
	v_add_f32_e32 v244, v184, v180
	v_add_f32_e32 v196, v185, v181
	v_add_f32_e32 v189, v186, v182
	v_fma_f32 v190, v134, v217, v191
	v_fma_f32 v203, v134, v195, v244
	v_fma_f32 v232, v134, v188, v196
	v_fma_f32 v208, v134, v200, v189
	v_fma_f32 v209, v135, v193, v190
	v_fma_f32 v210, v135, v194, v203
	v_fma_f32 v0, v135, v207, v232
	v_fma_f32 v173, v135, v236, v208
	v_lshlrev_b32_e32 v214, 16, v58
	v_and_b32_e32 v215, s100, v58
	v_lshlrev_b32_e32 v216, 16, v59
	v_and_b32_e32 v217, s100, v59
	v_add_f32_e32 v195, v214, v183
	v_add_f32_e32 v188, v215, v184
	v_add_f32_e32 v200, v216, v185
	v_add_f32_e32 v193, v217, v186
	v_fma_f32 v194, v134, v187, v195
	v_fma_f32 v207, v134, v199, v188
	v_fma_f32 v236, v134, v192, v200
	v_fma_f32 v221, v134, v245, v193
; __device__ __forceinline__ unsigned pk2(float lo, float hi) { return pg8::cvt_pk_bf16(lo, hi); }
; __global__ void __launch_bounds__(NTHR, 2) hybrid_fwd(Args args) {
;     ...
;             float a[8];
; #pragma unroll
;             for (int e = 0; e < 8; ++e) a[e] = 0.f;
;             const u32x4 u0 = qv[0];
; #pragma unroll
;             for (int j = 0; j < 16; ++j) { const float mk = j < cnt ? 1.0f : 0.0f; const u32x4 q = qv[j];
;                 a[0] += mk * bflo(q.x); a[1] += mk * bfhi(q.x); a[2] += mk * bflo(q.y); a[3] += mk * bfhi(q.y); a[4] += mk * bflo(q.z); a[5] += mk * bfhi(q.z); a[6] += mk * bflo(q.w); a[7] += mk * bfhi(q.w); }
;             const float ic = 1.0f / (float)cnt;
;             u32x4 o; o.x = pk2(a[0] * ic - bflo(u0.x), a[1] * ic - bfhi(u0.x)); o.y = pk2(a[2] * ic - bflo(u0.y), a[3] * ic - bfhi(u0.y));
;             o.z = pk2(a[4] * ic - bflo(u0.z), a[5] * ic - bfhi(u0.z)); o.w = pk2(a[6] * ic - bflo(u0.w), a[7] * ic - bfhi(u0.w));
;             *(u32x4*)(AD + (size_t)t * 1024 + lane * 8) = o; }
	v_fma_f32 v222, v135, v197, v194
	v_fma_f32 v223, v135, v198, v207
	v_fma_f32 v253, v135, v211, v236
	v_fma_f32 v179, v135, v240, v221
	v_lshlrev_b32_e32 v180, 16, v62
	v_and_b32_e32 v181, s100, v62
	v_lshlrev_b32_e32 v182, 16, v63
	v_and_b32_e32 v187, s100, v63
	v_add_f32_e32 v199, v180, v214
	v_add_f32_e32 v192, v181, v215
	v_add_f32_e32 v245, v182, v216
	v_add_f32_e32 v197, v187, v217
	v_fma_f32 v198, v134, v191, v199
	v_fma_f32 v211, v134, v244, v192
	v_fma_f32 v240, v134, v196, v245
	v_fma_f32 v225, v134, v189, v197
	v_fma_f32 v226, v135, v201, v198
	v_fma_f32 v227, v135, v202, v211
	v_fma_f32 v176, v135, v224, v240
	v_fma_f32 v183, v135, v249, v225
	v_lshlrev_b32_e32 v184, 16, v66
	v_and_b32_e32 v185, s100, v66
	v_lshlrev_b32_e32 v186, 16, v67
	v_and_b32_e32 v191, s100, v67
	v_add_f32_e32 v244, v184, v180
	v_add_f32_e32 v196, v185, v181
	v_add_f32_e32 v189, v186, v182
	v_add_f32_e32 v201, v191, v187
	v_fma_f32 v202, v134, v195, v244
	v_fma_f32 v224, v134, v188, v196
	v_fma_f32 v249, v134, v200, v189
	v_fma_f32 v229, v134, v193, v201
	v_fma_f32 v230, v135, v246, v202
	v_fma_f32 v231, v135, v247, v224
	v_fma_f32 v1, v135, v228, v249
	v_fma_f32 v214, v135, v204, v229
	v_lshlrev_b32_e32 v215, 16, v70
	v_and_b32_e32 v216, s100, v70
	v_lshlrev_b32_e32 v217, 16, v71
	v_and_b32_e32 v195, s100, v71
	v_add_f32_e32 v188, v215, v184
	v_add_f32_e32 v200, v216, v185
	v_add_f32_e32 v193, v217, v186
	v_add_f32_e32 v246, v195, v191
	v_fma_f32 v247, v134, v199, v188
	v_fma_f32 v228, v134, v192, v200
	v_fma_f32 v204, v134, v245, v193
	v_fma_f32 v233, v134, v197, v246
	v_fma_f32 v234, v135, v190, v247
	v_fma_f32 v235, v135, v203, v228
	v_fma_f32 v254, v135, v232, v204
	v_fma_f32 v180, v135, v208, v233
	v_fma_f32 v181, v136, v237, v234
	v_fma_f32 v182, v136, v238, v235
	v_fma_f32 v187, v136, v239, v254
	v_fma_f32 v199, v136, v177, v180
	s_add_i32 s101, s99, 1
	v_min_u32_e32 v192, s101, v137
	v_cvt_f32_u32_e32 v192, v192
	v_rcp_f32_e32 v192, v192
	s_nop 0
	v_fma_f32 v181, v181, v192, -v215
	v_fma_f32 v182, v182, v192, -v216
	v_fma_f32 v187, v187, v192, -v217
	v_fma_f32 v199, v199, v192, -v195
	v_cvt_pk_bf16_f32 v70, v181, v182
	v_cvt_pk_bf16_f32 v71, v187, v199
	global_store_dwordx4 v[138:139], v[68:71], off
	v_lshlrev_b32_e32 v245, 16, v74
	v_and_b32_e32 v197, s100, v74
	v_lshlrev_b32_e32 v190, 16, v75
	v_and_b32_e32 v203, s100, v75
	v_add_f32_e32 v232, v245, v215
	v_add_f32_e32 v208, v197, v216
	v_add_f32_e32 v237, v190, v217
	v_add_f32_e32 v238, v203, v195
	v_fma_f32 v239, v134, v244, v232
	v_fma_f32 v177, v134, v196, v208
	v_fma_f32 v181, v134, v189, v237
	v_fma_f32 v182, v134, v201, v238
	v_fma_f32 v187, v135, v194, v239
	v_fma_f32 v199, v135, v207, v177
	v_fma_f32 v192, v135, v236, v181
	v_fma_f32 v184, v135, v221, v182
	v_fma_f32 v185, v136, v241, v187
	v_fma_f32 v186, v136, v242, v199
	v_fma_f32 v191, v136, v243, v192
	v_fma_f32 v244, v136, v172, v184
	s_add_i32 s101, s99, 2
	v_min_u32_e32 v196, s101, v137
	v_cvt_f32_u32_e32 v196, v196
	v_rcp_f32_e32 v196, v196
	s_nop 0
	v_fma_f32 v185, v185, v196, -v245
	v_fma_f32 v186, v186, v196, -v197
	v_fma_f32 v191, v191, v196, -v190
	v_fma_f32 v244, v244, v196, -v203
	v_cvt_pk_bf16_f32 v74, v185, v186
	v_cvt_pk_bf16_f32 v75, v191, v244
	global_store_dwordx4 v[138:139], v[72:75], off offset:2048
	v_lshl_add_u64 v[138:139], v[138:139], 0, s[26:27]
	v_lshlrev_b32_e32 v189, 16, v78
	v_and_b32_e32 v201, s100, v78
	v_lshlrev_b32_e32 v194, 16, v79
	v_and_b32_e32 v207, s100, v79
	v_add_f32_e32 v236, v189, v245
	v_add_f32_e32 v221, v201, v197
	v_add_f32_e32 v241, v194, v190
	v_add_f32_e32 v242, v207, v203
	v_fma_f32 v243, v134, v188, v236
	v_fma_f32 v172, v134, v200, v221
	v_fma_f32 v185, v134, v193, v241
	v_fma_f32 v186, v134, v246, v242
	v_fma_f32 v191, v135, v198, v243
	v_fma_f32 v244, v135, v211, v172
	v_fma_f32 v196, v135, v240, v185
	v_fma_f32 v215, v135, v225, v186
	v_fma_f32 v216, v136, v250, v191
	v_fma_f32 v217, v136, v251, v244
	v_fma_f32 v195, v136, v252, v196
	v_fma_f32 v188, v136, v255, v215
	s_add_i32 s101, s99, 3
	v_min_u32_e32 v200, s101, v137
	v_cvt_f32_u32_e32 v200, v200
	v_rcp_f32_e32 v200, v200
	s_nop 0
	v_fma_f32 v216, v216, v200, -v189
	v_fma_f32 v217, v217, v200, -v201
	v_fma_f32 v195, v195, v200, -v194
	v_fma_f32 v188, v188, v200, -v207
	v_cvt_pk_bf16_f32 v78, v216, v217
	v_cvt_pk_bf16_f32 v79, v195, v188
	global_store_dwordx4 v[138:139], v[76:79], off
	v_lshlrev_b32_e32 v193, 16, v82
	v_and_b32_e32 v246, s100, v82
	v_lshlrev_b32_e32 v198, 16, v83
	v_and_b32_e32 v211, s100, v83
	v_add_f32_e32 v240, v193, v189
	v_add_f32_e32 v225, v246, v201
	v_add_f32_e32 v250, v198, v194
	v_add_f32_e32 v251, v211, v207
	v_fma_f32 v252, v134, v232, v240
	v_fma_f32 v255, v134, v208, v225
	v_fma_f32 v216, v134, v237, v250
	v_fma_f32 v217, v134, v238, v251
	v_fma_f32 v195, v135, v202, v252
	v_fma_f32 v188, v135, v224, v255
	v_fma_f32 v200, v135, v249, v216
	v_fma_f32 v245, v135, v229, v217
	v_fma_f32 v197, v136, v205, v195
	v_fma_f32 v190, v136, v206, v188
	v_fma_f32 v203, v136, v175, v200
	v_fma_f32 v232, v136, v178, v245
	s_add_i32 s101, s99, 4
	v_min_u32_e32 v208, s101, v137
	v_cvt_f32_u32_e32 v208, v208
	v_rcp_f32_e32 v208, v208
	s_nop 0
	v_fma_f32 v197, v197, v208, -v193
	v_fma_f32 v190, v190, v208, -v246
	v_fma_f32 v203, v203, v208, -v198
	v_fma_f32 v232, v232, v208, -v211
	v_cvt_pk_bf16_f32 v82, v197, v190
	v_cvt_pk_bf16_f32 v83, v203, v232
	global_store_dwordx4 v[138:139], v[80:83], off offset:2048
	v_lshl_add_u64 v[138:139], v[138:139], 0, s[26:27]
	v_lshlrev_b32_e32 v237, 16, v86
	v_and_b32_e32 v238, s100, v86
	v_lshlrev_b32_e32 v202, 16, v87
	v_and_b32_e32 v224, s100, v87
	v_add_f32_e32 v249, v237, v193
; __device__ __forceinline__ unsigned pk2(float lo, float hi) { return pg8::cvt_pk_bf16(lo, hi); }
; __global__ void __launch_bounds__(NTHR, 2) hybrid_fwd(Args args) {
;     ...
;             float a[8];
; #pragma unroll
;             for (int e = 0; e < 8; ++e) a[e] = 0.f;
;             const u32x4 u0 = qv[0];
; #pragma unroll
;             for (int j = 0; j < 16; ++j) { const float mk = j < cnt ? 1.0f : 0.0f; const u32x4 q = qv[j];
;                 a[0] += mk * bflo(q.x); a[1] += mk * bfhi(q.x); a[2] += mk * bflo(q.y); a[3] += mk * bfhi(q.y); a[4] += mk * bflo(q.z); a[5] += mk * bfhi(q.z); a[6] += mk * bflo(q.w); a[7] += mk * bfhi(q.w); }
;             const float ic = 1.0f / (float)cnt;
;             u32x4 o; o.x = pk2(a[0] * ic - bflo(u0.x), a[1] * ic - bfhi(u0.x)); o.y = pk2(a[2] * ic - bflo(u0.y), a[3] * ic - bfhi(u0.y));
;             o.z = pk2(a[4] * ic - bflo(u0.z), a[5] * ic - bfhi(u0.z)); o.w = pk2(a[6] * ic - bflo(u0.w), a[7] * ic - bfhi(u0.w));
;             *(u32x4*)(AD + (size_t)t * 1024 + lane * 8) = o; }
	v_add_f32_e32 v229, v238, v246
	v_add_f32_e32 v205, v202, v198
	v_add_f32_e32 v206, v224, v211
	v_fma_f32 v175, v134, v236, v249
	v_fma_f32 v178, v134, v221, v229
	v_fma_f32 v197, v134, v241, v205
	v_fma_f32 v190, v134, v242, v206
	v_fma_f32 v203, v135, v247, v175
	v_fma_f32 v232, v135, v228, v178
	v_fma_f32 v208, v135, v204, v197
	v_fma_f32 v189, v135, v233, v190
	v_fma_f32 v201, v136, v209, v203
	v_fma_f32 v194, v136, v210, v232
	v_fma_f32 v207, v136, v0, v208
	v_fma_f32 v236, v136, v173, v189
	s_add_i32 s101, s99, 5
	v_min_u32_e32 v221, s101, v137
	v_cvt_f32_u32_e32 v221, v221
	v_rcp_f32_e32 v221, v221
	s_nop 0
	v_fma_f32 v201, v201, v221, -v237
	v_fma_f32 v194, v194, v221, -v238
	v_fma_f32 v207, v207, v221, -v202
	v_fma_f32 v236, v236, v221, -v224
	v_cvt_pk_bf16_f32 v86, v201, v194
	v_cvt_pk_bf16_f32 v87, v207, v236
	global_store_dwordx4 v[138:139], v[84:87], off
	v_lshlrev_b32_e32 v241, 16, v90
	v_and_b32_e32 v242, s100, v90
	v_lshlrev_b32_e32 v247, 16, v91
	v_and_b32_e32 v228, s100, v91
	v_add_f32_e32 v204, v241, v237
	v_add_f32_e32 v233, v242, v238
	v_add_f32_e32 v209, v247, v202
	v_add_f32_e32 v210, v228, v224
	v_fma_f32 v0, v134, v240, v204
	v_fma_f32 v173, v134, v225, v233
	v_fma_f32 v201, v134, v250, v209
	v_fma_f32 v194, v134, v251, v210
	v_fma_f32 v207, v135, v239, v0
	v_fma_f32 v236, v135, v177, v173
	v_fma_f32 v221, v135, v181, v201
	v_fma_f32 v193, v135, v182, v194
	v_fma_f32 v246, v136, v222, v207
	v_fma_f32 v198, v136, v223, v236
	v_fma_f32 v211, v136, v253, v221
	v_fma_f32 v240, v136, v179, v193
	s_add_i32 s101, s99, 6
	v_min_u32_e32 v225, s101, v137
	v_cvt_f32_u32_e32 v225, v225
	v_rcp_f32_e32 v225, v225
	s_nop 0
	v_fma_f32 v246, v246, v225, -v241
	v_fma_f32 v198, v198, v225, -v242
	v_fma_f32 v211, v211, v225, -v247
	v_fma_f32 v240, v240, v225, -v228
	v_cvt_pk_bf16_f32 v90, v246, v198
	v_cvt_pk_bf16_f32 v91, v211, v240
	global_store_dwordx4 v[138:139], v[88:91], off offset:2048
	v_lshl_add_u64 v[138:139], v[138:139], 0, s[26:27]
	v_lshlrev_b32_e32 v250, 16, v94
	v_and_b32_e32 v251, s100, v94
	v_lshlrev_b32_e32 v239, 16, v95
	v_and_b32_e32 v177, s100, v95
	v_add_f32_e32 v181, v250, v241
	v_add_f32_e32 v182, v251, v242
	v_add_f32_e32 v222, v239, v247
	v_add_f32_e32 v223, v177, v228
	v_fma_f32 v253, v134, v249, v181
	v_fma_f32 v179, v134, v229, v182
	v_fma_f32 v246, v134, v205, v222
	v_fma_f32 v198, v134, v206, v223
	v_fma_f32 v211, v135, v243, v253
	v_fma_f32 v240, v135, v172, v179
	v_fma_f32 v225, v135, v185, v246
	v_fma_f32 v237, v135, v186, v198
	v_fma_f32 v238, v136, v226, v211
	v_fma_f32 v202, v136, v227, v240
	v_fma_f32 v224, v136, v176, v225
	v_fma_f32 v249, v136, v183, v237
	s_add_i32 s101, s99, 7
	v_min_u32_e32 v229, s101, v137
	v_cvt_f32_u32_e32 v229, v229
	v_rcp_f32_e32 v229, v229
	s_nop 0
	v_fma_f32 v238, v238, v229, -v250
	v_fma_f32 v202, v202, v229, -v251
	v_fma_f32 v224, v224, v229, -v239
	v_fma_f32 v249, v249, v229, -v177
	v_cvt_pk_bf16_f32 v94, v238, v202
	v_cvt_pk_bf16_f32 v95, v224, v249
	global_store_dwordx4 v[138:139], v[92:95], off
	v_lshlrev_b32_e32 v205, 16, v98
	v_and_b32_e32 v206, s100, v98
	v_lshlrev_b32_e32 v243, 16, v99
	v_and_b32_e32 v172, s100, v99
	v_add_f32_e32 v185, v205, v250
	v_add_f32_e32 v186, v206, v251
	v_add_f32_e32 v226, v243, v239
	v_add_f32_e32 v227, v172, v177
	v_fma_f32 v176, v134, v204, v185
	v_fma_f32 v183, v134, v233, v186
	v_fma_f32 v238, v134, v209, v226
	v_fma_f32 v202, v134, v210, v227
	v_fma_f32 v224, v135, v252, v176
	v_fma_f32 v249, v135, v255, v183
	v_fma_f32 v229, v135, v216, v238
	v_fma_f32 v241, v135, v217, v202
	v_fma_f32 v242, v136, v230, v224
	v_fma_f32 v247, v136, v231, v249
	v_fma_f32 v228, v136, v1, v229
	v_fma_f32 v204, v136, v214, v241
	s_add_i32 s101, s99, 8
	v_min_u32_e32 v233, s101, v137
	v_cvt_f32_u32_e32 v233, v233
	v_rcp_f32_e32 v233, v233
	s_nop 0
	v_fma_f32 v242, v242, v233, -v205
	v_fma_f32 v247, v247, v233, -v206
	v_fma_f32 v228, v228, v233, -v243
	v_fma_f32 v204, v204, v233, -v172
	v_cvt_pk_bf16_f32 v98, v242, v247
	v_cvt_pk_bf16_f32 v99, v228, v204
	global_store_dwordx4 v[138:139], v[96:99], off offset:2048
	v_lshl_add_u64 v[138:139], v[138:139], 0, s[26:27]
	v_lshlrev_b32_e32 v209, 16, v102
	v_and_b32_e32 v210, s100, v102
	v_lshlrev_b32_e32 v252, 16, v103
	v_and_b32_e32 v255, s100, v103
	v_add_f32_e32 v216, v209, v205
	v_add_f32_e32 v217, v210, v206
	v_add_f32_e32 v230, v252, v243
	v_add_f32_e32 v231, v255, v172
	v_fma_f32 v1, v134, v181, v216
	v_fma_f32 v214, v134, v182, v217
	v_fma_f32 v242, v134, v222, v230
	v_fma_f32 v247, v134, v223, v231
	v_fma_f32 v228, v135, v175, v1
	v_fma_f32 v204, v135, v178, v214
	v_fma_f32 v233, v135, v197, v242
	v_fma_f32 v250, v135, v190, v247
	v_fma_f32 v251, v136, v234, v228
	v_fma_f32 v239, v136, v235, v204
	v_fma_f32 v177, v136, v254, v233
	v_fma_f32 v181, v136, v180, v250
	s_add_i32 s101, s99, 9
	v_min_u32_e32 v182, s101, v137
	v_cvt_f32_u32_e32 v182, v182
	v_rcp_f32_e32 v182, v182
	s_nop 0
	v_fma_f32 v251, v251, v182, -v209
	v_fma_f32 v239, v239, v182, -v210
	v_fma_f32 v177, v177, v182, -v252
	v_fma_f32 v181, v181, v182, -v255
	v_cvt_pk_bf16_f32 v102, v251, v239
	v_cvt_pk_bf16_f32 v103, v177, v181
	global_store_dwordx4 v[138:139], v[100:103], off
	v_lshlrev_b32_e32 v222, 16, v106
	v_and_b32_e32 v223, s100, v106
	v_lshlrev_b32_e32 v175, 16, v107
	v_and_b32_e32 v178, s100, v107
	v_add_f32_e32 v197, v222, v209
	v_add_f32_e32 v190, v223, v210
	v_add_f32_e32 v234, v175, v252
	v_add_f32_e32 v235, v178, v255
	v_fma_f32 v254, v134, v185, v197
	v_fma_f32 v180, v134, v186, v190
	v_fma_f32 v251, v134, v226, v234
	v_fma_f32 v239, v134, v227, v235
	v_fma_f32 v177, v135, v0, v254
	v_fma_f32 v181, v135, v173, v180
; __device__ __forceinline__ unsigned pk2(float lo, float hi) { return pg8::cvt_pk_bf16(lo, hi); }
; __global__ void __launch_bounds__(NTHR, 2) hybrid_fwd(Args args) {
;     ...
;             float a[8];
; #pragma unroll
;             for (int e = 0; e < 8; ++e) a[e] = 0.f;
;             const u32x4 u0 = qv[0];
; #pragma unroll
;             for (int j = 0; j < 16; ++j) { const float mk = j < cnt ? 1.0f : 0.0f; const u32x4 q = qv[j];
;                 a[0] += mk * bflo(q.x); a[1] += mk * bfhi(q.x); a[2] += mk * bflo(q.y); a[3] += mk * bfhi(q.y); a[4] += mk * bflo(q.z); a[5] += mk * bfhi(q.z); a[6] += mk * bflo(q.w); a[7] += mk * bfhi(q.w); }
;             const float ic = 1.0f / (float)cnt;
;             u32x4 o; o.x = pk2(a[0] * ic - bflo(u0.x), a[1] * ic - bfhi(u0.x)); o.y = pk2(a[2] * ic - bflo(u0.y), a[3] * ic - bfhi(u0.y));
;             o.z = pk2(a[4] * ic - bflo(u0.z), a[5] * ic - bfhi(u0.z)); o.w = pk2(a[6] * ic - bflo(u0.w), a[7] * ic - bfhi(u0.w));
;             *(u32x4*)(AD + (size_t)t * 1024 + lane * 8) = o; }
	v_fma_f32 v182, v135, v201, v251
	v_fma_f32 v205, v135, v194, v239
	v_fma_f32 v206, v136, v187, v177
	v_fma_f32 v243, v136, v199, v181
	v_fma_f32 v172, v136, v192, v182
	v_fma_f32 v185, v136, v184, v205
	s_add_i32 s101, s99, 10
	v_min_u32_e32 v186, s101, v137
	v_cvt_f32_u32_e32 v186, v186
	v_rcp_f32_e32 v186, v186
	s_nop 0
	v_fma_f32 v206, v206, v186, -v222
	v_fma_f32 v243, v243, v186, -v223
	v_fma_f32 v172, v172, v186, -v175
	v_fma_f32 v185, v185, v186, -v178
	v_cvt_pk_bf16_f32 v106, v206, v243
	v_cvt_pk_bf16_f32 v107, v172, v185
	global_store_dwordx4 v[138:139], v[104:107], off offset:2048
	v_lshl_add_u64 v[138:139], v[138:139], 0, s[26:27]
	v_lshlrev_b32_e32 v226, 16, v110
	v_and_b32_e32 v227, s100, v110
	v_lshlrev_b32_e32 v0, 16, v111
	v_and_b32_e32 v173, s100, v111
	v_add_f32_e32 v201, v226, v222
	v_add_f32_e32 v194, v227, v223
	v_add_f32_e32 v187, v0, v175
	v_add_f32_e32 v199, v173, v178
	v_fma_f32 v192, v134, v216, v201
	v_fma_f32 v184, v134, v217, v194
	v_fma_f32 v206, v134, v230, v187
	v_fma_f32 v243, v134, v231, v199
	v_fma_f32 v172, v135, v253, v192
	v_fma_f32 v185, v135, v179, v184
	v_fma_f32 v186, v135, v246, v206
	v_fma_f32 v209, v135, v198, v243
	v_fma_f32 v210, v136, v191, v172
	v_fma_f32 v252, v136, v244, v185
	v_fma_f32 v255, v136, v196, v186
	v_fma_f32 v216, v136, v215, v209
	s_add_i32 s101, s99, 11
	v_min_u32_e32 v217, s101, v137
	v_cvt_f32_u32_e32 v217, v217
	v_rcp_f32_e32 v217, v217
	s_nop 0
	v_fma_f32 v210, v210, v217, -v226
	v_fma_f32 v252, v252, v217, -v227
	v_fma_f32 v255, v255, v217, -v0
	v_fma_f32 v216, v216, v217, -v173
	v_cvt_pk_bf16_f32 v110, v210, v252
	v_cvt_pk_bf16_f32 v111, v255, v216
	global_store_dwordx4 v[138:139], v[108:111], off
	v_lshlrev_b32_e32 v230, 16, v114
	v_and_b32_e32 v231, s100, v114
	v_lshlrev_b32_e32 v253, 16, v115
	v_and_b32_e32 v179, s100, v115
	v_add_f32_e32 v246, v230, v226
	v_add_f32_e32 v198, v231, v227
	v_add_f32_e32 v191, v253, v0
	v_add_f32_e32 v244, v179, v173
	v_fma_f32 v196, v134, v197, v246
	v_fma_f32 v215, v134, v190, v198
	v_fma_f32 v210, v134, v234, v191
	v_fma_f32 v252, v134, v235, v244
	v_fma_f32 v255, v135, v176, v196
	v_fma_f32 v216, v135, v183, v215
	v_fma_f32 v217, v135, v238, v210
	v_fma_f32 v222, v135, v202, v252
	v_fma_f32 v223, v136, v195, v255
	v_fma_f32 v175, v136, v188, v216
	v_fma_f32 v178, v136, v200, v217
	v_fma_f32 v197, v136, v245, v222
	s_add_i32 s101, s99, 12
	v_min_u32_e32 v190, s101, v137
	v_cvt_f32_u32_e32 v190, v190
	v_rcp_f32_e32 v190, v190
	s_nop 0
	v_fma_f32 v223, v223, v190, -v230
	v_fma_f32 v175, v175, v190, -v231
	v_fma_f32 v178, v178, v190, -v253
	v_fma_f32 v197, v197, v190, -v179
	v_cvt_pk_bf16_f32 v114, v223, v175
	v_cvt_pk_bf16_f32 v115, v178, v197
	global_store_dwordx4 v[138:139], v[112:115], off offset:2048
	v_lshl_add_u64 v[138:139], v[138:139], 0, s[26:27]
	v_lshlrev_b32_e32 v234, 16, v118
	v_and_b32_e32 v235, s100, v118
	v_lshlrev_b32_e32 v176, 16, v119
	v_and_b32_e32 v183, s100, v119
	v_add_f32_e32 v238, v234, v230
	v_add_f32_e32 v202, v235, v231
	v_add_f32_e32 v195, v176, v253
	v_add_f32_e32 v188, v183, v179
	v_fma_f32 v200, v134, v201, v238
	v_fma_f32 v245, v134, v194, v202
	v_fma_f32 v223, v134, v187, v195
	v_fma_f32 v175, v134, v199, v188
	v_fma_f32 v178, v135, v1, v200
	v_fma_f32 v197, v135, v214, v245
	v_fma_f32 v190, v135, v242, v223
	v_fma_f32 v226, v135, v247, v175
	v_fma_f32 v227, v136, v203, v178
	v_fma_f32 v0, v136, v232, v197
	v_fma_f32 v173, v136, v208, v190
	v_fma_f32 v201, v136, v189, v226
	s_add_i32 s101, s99, 13
	v_min_u32_e32 v194, s101, v137
	v_cvt_f32_u32_e32 v194, v194
	v_rcp_f32_e32 v194, v194
	s_nop 0
	v_fma_f32 v227, v227, v194, -v234
	v_fma_f32 v0, v0, v194, -v235
	v_fma_f32 v173, v173, v194, -v176
	v_fma_f32 v201, v201, v194, -v183
	v_cvt_pk_bf16_f32 v118, v227, v0
	v_cvt_pk_bf16_f32 v119, v173, v201
	global_store_dwordx4 v[138:139], v[116:119], off
	v_lshlrev_b32_e32 v187, 16, v122
	v_and_b32_e32 v199, s100, v122
	v_lshlrev_b32_e32 v1, 16, v123
	v_and_b32_e32 v214, s100, v123
	v_add_f32_e32 v242, v187, v234
	v_add_f32_e32 v247, v199, v235
	v_add_f32_e32 v203, v1, v176
	v_add_f32_e32 v232, v214, v183
	v_fma_f32 v208, v134, v246, v242
	v_fma_f32 v189, v134, v198, v247
	v_fma_f32 v227, v134, v191, v203
	v_fma_f32 v0, v134, v244, v232
	v_fma_f32 v173, v135, v254, v208
	v_fma_f32 v201, v135, v180, v189
	v_fma_f32 v194, v135, v251, v227
	v_fma_f32 v230, v135, v239, v0
	v_fma_f32 v231, v136, v207, v173
	v_fma_f32 v253, v136, v236, v201
	v_fma_f32 v179, v136, v221, v194
	v_fma_f32 v246, v136, v193, v230
	s_add_i32 s101, s99, 14
	v_min_u32_e32 v198, s101, v137
	v_cvt_f32_u32_e32 v198, v198
	v_rcp_f32_e32 v198, v198
	s_nop 0
	v_fma_f32 v231, v231, v198, -v187
	v_fma_f32 v253, v253, v198, -v199
	v_fma_f32 v179, v179, v198, -v1
	v_fma_f32 v246, v246, v198, -v214
	v_cvt_pk_bf16_f32 v122, v231, v253
	v_cvt_pk_bf16_f32 v123, v179, v246
	global_store_dwordx4 v[138:139], v[120:123], off offset:2048
	v_lshl_add_u64 v[138:139], v[138:139], 0, s[26:27]
	v_lshlrev_b32_e32 v191, 16, v126
	v_and_b32_e32 v244, s100, v126
	v_lshlrev_b32_e32 v254, 16, v127
	v_and_b32_e32 v180, s100, v127
	v_add_f32_e32 v251, v191, v187
	v_add_f32_e32 v239, v244, v199
	v_add_f32_e32 v207, v254, v1
	v_add_f32_e32 v236, v180, v214
	v_fma_f32 v221, v134, v238, v251
	v_fma_f32 v193, v134, v202, v239
	v_fma_f32 v231, v134, v195, v207
	v_fma_f32 v253, v134, v188, v236
	v_fma_f32 v179, v135, v192, v221
	v_fma_f32 v246, v135, v184, v193
	v_fma_f32 v198, v135, v206, v231
	v_fma_f32 v234, v135, v243, v253
	v_fma_f32 v235, v136, v211, v179
	v_fma_f32 v176, v136, v240, v246
	v_fma_f32 v183, v136, v225, v198
	v_fma_f32 v238, v136, v237, v234
	s_add_i32 s101, s99, 15
; __device__ __forceinline__ unsigned pk2(float lo, float hi) { return pg8::cvt_pk_bf16(lo, hi); }
; __global__ void __launch_bounds__(NTHR, 2) hybrid_fwd(Args args) {
;     ...
;             for (int j = 0; j < 16; ++j) { const float mk = j < cnt ? 1.0f : 0.0f; const u32x4 q = qv[j];
;                 a[0] += mk * bflo(q.x); a[1] += mk * bfhi(q.x); a[2] += mk * bflo(q.y); a[3] += mk * bfhi(q.y); a[4] += mk * bflo(q.z); a[5] += mk * bfhi(q.z); a[6] += mk * bflo(q.w); a[7] += mk * bfhi(q.w); }
;             const float ic = 1.0f / (float)cnt;
;             u32x4 o; o.x = pk2(a[0] * ic - bflo(u0.x), a[1] * ic - bfhi(u0.x)); o.y = pk2(a[2] * ic - bflo(u0.y), a[3] * ic - bfhi(u0.y));
;             o.z = pk2(a[4] * ic - bflo(u0.z), a[5] * ic - bfhi(u0.z)); o.w = pk2(a[6] * ic - bflo(u0.w), a[7] * ic - bfhi(u0.w));
;             *(u32x4*)(AD + (size_t)t * 1024 + lane * 8) = o; }
	v_min_u32_e32 v202, s101, v137
	v_cvt_f32_u32_e32 v202, v202
	v_rcp_f32_e32 v202, v202
	s_nop 0
	v_fma_f32 v235, v235, v202, -v191
	v_fma_f32 v176, v176, v202, -v244
	v_fma_f32 v183, v183, v202, -v254
	v_fma_f32 v238, v238, v202, -v180
	v_cvt_pk_bf16_f32 v126, v235, v176
	v_cvt_pk_bf16_f32 v127, v183, v238
	global_store_dwordx4 v[138:139], v[124:127], off
	v_lshlrev_b32_e32 v195, 16, v130
	v_and_b32_e32 v188, s100, v130
	v_lshlrev_b32_e32 v192, 16, v131
	v_and_b32_e32 v184, s100, v131
	v_add_f32_e32 v206, v195, v191
	v_add_f32_e32 v243, v188, v244
	v_add_f32_e32 v211, v192, v254
	v_add_f32_e32 v240, v184, v180
	v_fma_f32 v225, v134, v242, v206
	v_fma_f32 v237, v134, v247, v243
	v_fma_f32 v235, v134, v203, v211
	v_fma_f32 v176, v134, v232, v240
	v_fma_f32 v183, v135, v196, v225
	v_fma_f32 v238, v135, v215, v237
	v_fma_f32 v202, v135, v210, v235
	v_fma_f32 v187, v135, v252, v176
	v_fma_f32 v199, v136, v224, v183
	v_fma_f32 v1, v136, v249, v238
	v_fma_f32 v214, v136, v229, v202
	v_fma_f32 v242, v136, v241, v187
	s_add_i32 s101, s99, 16
	v_min_u32_e32 v247, s101, v137
	v_cvt_f32_u32_e32 v247, v247
	v_rcp_f32_e32 v247, v247
	s_nop 0
	v_fma_f32 v199, v199, v247, -v195
	v_fma_f32 v1, v1, v247, -v188
	v_fma_f32 v214, v214, v247, -v192
	v_fma_f32 v242, v242, v247, -v184
	v_cvt_pk_bf16_f32 v130, v199, v1
	v_cvt_pk_bf16_f32 v131, v214, v242
	global_store_dwordx4 v[138:139], v[128:131], off offset:2048
	s_branch .LBB0_377
; __global__ void __launch_bounds__(NTHR, 2) hybrid_fwd(Args args) {
;     ...
;         if (nr > 0) { const int sp0 = t_b & 2047, c0_ = (sp0 + 1) < w ? (sp0 + 1) : w;
; #pragma unroll
;             for (int j = 0; j < 16; ++j) qn[j] = *(const u32x4*)(UB + (size_t)(j < c0_ ? t_b - j : t_b) * 512 + lane * 8); }
;         for (int i = 0; i < nr; ++i) { const int t = t_b + i;
;             const int sp = t & 2047, cnt = (sp + 1) < w ? (sp + 1) : w;
;             u32x4 qv[16];
; #pragma unroll
;             for (int j = 0; j < 16; ++j) qv[j] = qn[j];
;             if (i + 1 < nr) { const int t1 = t + 1, sp1 = t1 & 2047, c1_ = (sp1 + 1) < w ? (sp1 + 1) : w;
; #pragma unroll
;                 for (int j = 0; j < 16; ++j) qn[j] = *(const u32x4*)(UB + (size_t)(j < c1_ ? t1 - j : t1) * 512 + lane * 8); }
.Lpool_orig:
	v_ashrrev_i32_e32 v1, 4, v0
	s_and_b32 s11, s10, 0x7ff
	v_lshlrev_b32_e64 v132, v1, 2
	s_add_i32 s11, s11, 1
	v_min_i32_e32 v6, s11, v132
	v_lshlrev_b32_e32 v0, 3, v0
	v_ashrrev_i32_e32 v1, 31, v0
	s_waitcnt vmcnt(0)
	v_mov_b32_e32 v4, s10
	v_cmp_lt_i32_e32 vcc, 1, v6
	v_lshl_add_u64 v[0:1], v[0:1], 1, s[8:9]
	s_mov_b64 s[14:15], 0x15c00000
	s_ashr_i32 s11, s10, 31
	v_subbrev_co_u32_e32 v4, vcc, 0, v4, vcc
	v_lshl_add_u64 v[128:129], v[0:1], 0, s[14:15]
	s_lshl_b64 s[14:15], s[10:11], 10
	v_ashrrev_i32_e32 v5, 31, v4
	v_lshl_add_u64 v[2:3], v[128:129], 0, s[14:15]
	v_lshlrev_b64 v[4:5], 10, v[4:5]
	v_cmp_lt_i32_e32 vcc, 2, v6
	v_lshl_add_u64 v[4:5], v[128:129], 0, v[4:5]
	global_load_dwordx4 v[124:127], v[2:3], off
	global_load_dwordx4 v[120:123], v[4:5], off
	v_cndmask_b32_e64 v2, 0, -2, vcc
	v_cmp_lt_i32_e32 vcc, 3, v6
	v_add_u32_e32 v2, s10, v2
	v_ashrrev_i32_e32 v3, 31, v2
	v_cndmask_b32_e64 v4, 0, -3, vcc
	v_add_u32_e32 v4, s10, v4
	v_lshlrev_b64 v[2:3], 10, v[2:3]
	v_ashrrev_i32_e32 v5, 31, v4
	v_lshl_add_u64 v[2:3], v[128:129], 0, v[2:3]
	v_lshlrev_b64 v[4:5], 10, v[4:5]
	v_cmp_lt_i32_e32 vcc, 4, v6
	v_lshl_add_u64 v[4:5], v[128:129], 0, v[4:5]
	global_load_dwordx4 v[116:119], v[2:3], off
	global_load_dwordx4 v[112:115], v[4:5], off
	v_cndmask_b32_e64 v2, 0, -4, vcc
	v_cmp_lt_i32_e32 vcc, 5, v6
	v_add_u32_e32 v2, s10, v2
	v_ashrrev_i32_e32 v3, 31, v2
	v_cndmask_b32_e64 v4, 0, -5, vcc
	v_add_u32_e32 v4, s10, v4
	v_lshlrev_b64 v[2:3], 10, v[2:3]
	v_ashrrev_i32_e32 v5, 31, v4
	v_lshl_add_u64 v[2:3], v[128:129], 0, v[2:3]
	v_lshlrev_b64 v[4:5], 10, v[4:5]
	v_cmp_lt_i32_e32 vcc, 6, v6
	v_lshl_add_u64 v[4:5], v[128:129], 0, v[4:5]
	global_load_dwordx4 v[108:111], v[2:3], off
	global_load_dwordx4 v[104:107], v[4:5], off
	v_cndmask_b32_e64 v2, 0, -6, vcc
	v_cmp_lt_i32_e32 vcc, 7, v6
	v_add_u32_e32 v2, s10, v2
	v_ashrrev_i32_e32 v3, 31, v2
	v_cndmask_b32_e64 v4, 0, -7, vcc
	v_add_u32_e32 v4, s10, v4
	v_lshlrev_b64 v[2:3], 10, v[2:3]
	v_ashrrev_i32_e32 v5, 31, v4
	v_lshl_add_u64 v[2:3], v[128:129], 0, v[2:3]
	v_lshlrev_b64 v[4:5], 10, v[4:5]
	v_cmp_lt_i32_e32 vcc, 8, v6
	v_lshl_add_u64 v[4:5], v[128:129], 0, v[4:5]
	global_load_dwordx4 v[100:103], v[2:3], off
	global_load_dwordx4 v[96:99], v[4:5], off
	v_cndmask_b32_e64 v2, 0, -8, vcc
	v_cmp_lt_i32_e32 vcc, 9, v6
	v_add_u32_e32 v2, s10, v2
	v_ashrrev_i32_e32 v3, 31, v2
	v_cndmask_b32_e64 v4, 0, -9, vcc
	v_add_u32_e32 v4, s10, v4
	v_lshlrev_b64 v[2:3], 10, v[2:3]
	v_ashrrev_i32_e32 v5, 31, v4
	v_lshl_add_u64 v[2:3], v[128:129], 0, v[2:3]
	v_lshlrev_b64 v[4:5], 10, v[4:5]
	v_cmp_lt_i32_e32 vcc, 10, v6
	v_lshl_add_u64 v[4:5], v[128:129], 0, v[4:5]
	global_load_dwordx4 v[88:91], v[2:3], off
	global_load_dwordx4 v[92:95], v[4:5], off
	v_cndmask_b32_e64 v2, 0, -10, vcc
	v_cmp_lt_i32_e32 vcc, 11, v6
	v_add_u32_e32 v2, s10, v2
	v_ashrrev_i32_e32 v3, 31, v2
	v_cndmask_b32_e64 v4, 0, -11, vcc
	v_add_u32_e32 v4, s10, v4
	v_lshlrev_b64 v[2:3], 10, v[2:3]
	v_ashrrev_i32_e32 v5, 31, v4
	v_lshl_add_u64 v[2:3], v[128:129], 0, v[2:3]
	v_lshlrev_b64 v[4:5], 10, v[4:5]
	v_cmp_lt_i32_e32 vcc, 12, v6
	v_lshl_add_u64 v[4:5], v[128:129], 0, v[4:5]
	global_load_dwordx4 v[64:67], v[2:3], off
	global_load_dwordx4 v[68:71], v[4:5], off
	v_cndmask_b32_e64 v2, 0, -12, vcc
	v_cmp_lt_i32_e32 vcc, 13, v6
	v_add_u32_e32 v2, s10, v2
	v_ashrrev_i32_e32 v3, 31, v2
	v_cndmask_b32_e64 v4, 0, -13, vcc
	v_add_u32_e32 v4, s10, v4
	v_lshlrev_b64 v[2:3], 10, v[2:3]
	v_ashrrev_i32_e32 v5, 31, v4
	v_lshl_add_u64 v[2:3], v[128:129], 0, v[2:3]
	v_lshlrev_b64 v[4:5], 10, v[4:5]
	v_cmp_lt_i32_e32 vcc, 14, v6
	v_lshl_add_u64 v[4:5], v[128:129], 0, v[4:5]
	global_load_dwordx4 v[40:43], v[2:3], off
	global_load_dwordx4 v[44:47], v[4:5], off
	v_cndmask_b32_e64 v2, 0, -14, vcc
	v_cmp_lt_i32_e32 vcc, 15, v6
	v_add_u32_e32 v2, s10, v2
	v_ashrrev_i32_e32 v3, 31, v2
	v_cndmask_b32_e64 v4, 0, -15, vcc
	v_add_u32_e32 v4, s10, v4
	v_lshlrev_b64 v[2:3], 10, v[2:3]
	v_ashrrev_i32_e32 v5, 31, v4
	v_lshl_add_u64 v[2:3], v[128:129], 0, v[2:3]
	v_lshlrev_b64 v[4:5], 10, v[4:5]
	v_lshl_add_u64 v[4:5], v[128:129], 0, v[4:5]
	global_load_dwordx4 v[16:19], v[2:3], off
	global_load_dwordx4 v[20:23], v[4:5], off
	s_mov_b64 s[14:15], 0x3c00000
	v_lshl_add_u64 v[130:131], v[0:1], 0, s[14:15]
	v_cmp_lt_i32_e32 vcc, 0, v132
	s_waitcnt vmcnt(15)
	v_mov_b64_e32 v[0:1], v[124:125]
	s_waitcnt vmcnt(14)
	v_mov_b64_e32 v[4:5], v[120:121]
	s_waitcnt vmcnt(13)
	v_mov_b64_e32 v[8:9], v[116:117]
	s_waitcnt vmcnt(12)
	v_mov_b64_e32 v[12:13], v[112:113]
	v_cndmask_b32_e64 v133, 0, 1.0, vcc
	v_mov_b64_e32 v[2:3], v[126:127]
	v_mov_b64_e32 v[6:7], v[122:123]
	v_mov_b64_e32 v[10:11], v[118:119]
	v_mov_b64_e32 v[14:15], v[114:115]
	s_waitcnt vmcnt(11)
	v_mov_b64_e32 v[24:25], v[108:109]
	s_waitcnt vmcnt(10)
	v_mov_b64_e32 v[28:29], v[104:105]
	v_mov_b64_e32 v[26:27], v[110:111]
	v_mov_b64_e32 v[30:31], v[106:107]
	s_waitcnt vmcnt(9)
	v_mov_b64_e32 v[32:33], v[100:101]
	s_waitcnt vmcnt(8)
	v_mov_b64_e32 v[36:37], v[96:97]
	v_mov_b64_e32 v[34:35], v[102:103]
	v_mov_b64_e32 v[38:39], v[98:99]
	s_waitcnt vmcnt(7)
	v_mov_b64_e32 v[48:49], v[88:89]
	s_waitcnt vmcnt(6)
	v_mov_b64_e32 v[52:53], v[92:93]
	v_mov_b64_e32 v[50:51], v[90:91]
	v_mov_b64_e32 v[54:55], v[94:95]
	s_waitcnt vmcnt(5)
	v_mov_b64_e32 v[56:57], v[64:65]
	s_waitcnt vmcnt(4)
	v_mov_b64_e32 v[60:61], v[68:69]
	v_mov_b64_e32 v[58:59], v[66:67]
	v_mov_b64_e32 v[62:63], v[70:71]
	s_waitcnt vmcnt(3)
	v_mov_b64_e32 v[74:75], v[42:43]
	s_waitcnt vmcnt(2)
	v_mov_b64_e32 v[78:79], v[46:47]
	v_mov_b64_e32 v[72:73], v[40:41]
	v_mov_b64_e32 v[76:77], v[44:45]
	s_waitcnt vmcnt(1)
	v_mov_b64_e32 v[82:83], v[18:19]
	s_waitcnt vmcnt(0)
	v_mov_b64_e32 v[86:87], v[22:23]
	v_mov_b64_e32 v[80:81], v[16:17]
	v_mov_b64_e32 v[84:85], v[20:21]
	s_branch .LBB0_375

; __global__ void __launch_bounds__(NTHR, 2) hybrid_fwd(Args args) {
	.amdhsa_kernel _Z10hybrid_fwd4Args
		.amdhsa_group_segment_fixed_size 0
		.amdhsa_private_segment_fixed_size 0
		.amdhsa_kernarg_size 432
		.amdhsa_user_sgpr_count 2
		.amdhsa_user_sgpr_dispatch_ptr 0
		.amdhsa_user_sgpr_queue_ptr 0
		.amdhsa_user_sgpr_kernarg_segment_ptr 1
		.amdhsa_user_sgpr_dispatch_id 0
		.amdhsa_user_sgpr_kernarg_preload_length 0
		.amdhsa_user_sgpr_kernarg_preload_offset 0
		.amdhsa_user_sgpr_private_segment_size 0
		.amdhsa_uses_dynamic_stack 0
		.amdhsa_enable_private_segment 0
		.amdhsa_system_sgpr_workgroup_id_x 1
		.amdhsa_system_sgpr_workgroup_id_y 0
		.amdhsa_system_sgpr_workgroup_id_z 0
		.amdhsa_system_sgpr_workgroup_info 0
		.amdhsa_system_vgpr_workitem_id 2
		.amdhsa_next_free_vgpr 256
		.amdhsa_next_free_sgpr 102
		.amdhsa_accum_offset 256
		.amdhsa_reserve_vcc 1
		.amdhsa_float_round_mode_32 0
		.amdhsa_float_round_mode_16_64 0
		.amdhsa_float_denorm_mode_32 3
		.amdhsa_float_denorm_mode_16_64 3
		.amdhsa_dx10_clamp 1
		.amdhsa_ieee_mode 1
		.amdhsa_fp16_overflow 0
		.amdhsa_tg_split 0
		.amdhsa_exception_fp_ieee_invalid_op 0
		.amdhsa_exception_fp_denorm_src 0
		.amdhsa_exception_fp_ieee_div_zero 0
		.amdhsa_exception_fp_ieee_overflow 0
		.amdhsa_exception_fp_ieee_underflow 0
		.amdhsa_exception_fp_ieee_inexact 0
		.amdhsa_exception_int_div_zero 0
	.end_amdhsa_kernel

; __global__ void __launch_bounds__(NTHR, 2) hybrid_fwd(Args args) {
amdhsa.kernels:
  - .agpr_count:     0
    .args:
      - .offset:         0
        .size:           176
        .value_kind:     by_value
      - .offset:         176
        .size:           4
        .value_kind:     hidden_block_count_x
      - .offset:         180
        .size:           4
        .value_kind:     hidden_block_count_y
      - .offset:         184
        .size:           4
        .value_kind:     hidden_block_count_z
      - .offset:         188
        .size:           2
        .value_kind:     hidden_group_size_x
      - .offset:         190
        .size:           2
        .value_kind:     hidden_group_size_y
      - .offset:         192
        .size:           2
        .value_kind:     hidden_group_size_z
      - .offset:         194
        .size:           2
        .value_kind:     hidden_remainder_x
      - .offset:         196
        .size:           2
        .value_kind:     hidden_remainder_y
      - .offset:         198
        .size:           2
        .value_kind:     hidden_remainder_z
      - .offset:         216
        .size:           8
        .value_kind:     hidden_global_offset_x
      - .offset:         224
        .size:           8
        .value_kind:     hidden_global_offset_y
      - .offset:         232
        .size:           8
        .value_kind:     hidden_global_offset_z
      - .offset:         240
        .size:           2
        .value_kind:     hidden_grid_dims
      - .offset:         264
        .size:           8
        .value_kind:     hidden_multigrid_sync_arg
      - .offset:         296
        .size:           4
        .value_kind:     hidden_dynamic_lds_size
    .group_segment_fixed_size: 0
    .kernarg_segment_align: 8
    .kernarg_segment_size: 432
    .language:       OpenCL C
    .language_version:
      - 2
      - 0
    .max_flat_workgroup_size: 512
    .name:           _Z10hybrid_fwd4Args
    .private_segment_fixed_size: 0
    .sgpr_count:     108
    .sgpr_spill_count: 6
    .symbol:         _Z10hybrid_fwd4Args.kd
    .uniform_work_group_size: 1
    .uses_dynamic_stack: false
    .vgpr_count:     256
    .vgpr_spill_count: 0
    .wavefront_size: 64
